# GEMM tiles: first K-loop iteration peeled, first MFMA into each accumulator quad takes C=0, per-tile clearing of the 128 accumulator registers removed; loop heads kept at their previous byte phase
# baseline (speedup 1.0000x reference)
; #define PG8_STAGE(bufoff, gbase, voff) do { _Pragma("unroll") for (int _i = 0; _i < 2; ++_i) \
;         __builtin_amdgcn_global_load_lds((const unsigned*)((const char*)(gbase) + (voff)[_i]), (PG8_LAS unsigned*)(lds + (bufoff) + ldsw + _i * 8192), 16, 0, 0); } while (0)
; #define PG8_LDA(dst, b, h) do { _Pragma("unroll") for (int m = 0; m < 4; ++m) _Pragma("unroll") for (int k = 0; k < 2; ++k) dst[m][k] = *(const PG8_LAS bf16x8*)(lds + PG8_SA(b, h) + aoff + m * 2048 + k * 1024); } while (0)
; #define PG8_LDB(dst, b, h) do { _Pragma("unroll") for (int n = 0; n < 2; ++n) _Pragma("unroll") for (int k = 0; k < 2; ++k) dst[n][k] = *(const PG8_LAS bf16x8*)(lds + PG8_SB(b, h) + boff + n * 2048 + k * 1024); } while (0)
; #define PG8_MMA(ai, bj, At, Bt) do { __builtin_amdgcn_s_setprio(1); _Pragma("unroll") for (int m = 0; m < 4; ++m) _Pragma("unroll") for (int n = 0; n < 2; ++n) _Pragma("unroll") for (int k = 0; k < 2; ++k) \
;         acc[ai][bj][m][n] = __builtin_amdgcn_mfma_f32_16x16x32_bf16(Bt[n][k], At[m][k], acc[ai][bj][m][n], 0, 0, 0); __builtin_amdgcn_s_setprio(0); } while (0)
; #define PG8_WAIT_V(n) asm volatile("s_waitcnt vmcnt(" #n ")" ::: "memory")
; #define PG8_WAIT_L(n) asm volatile("s_waitcnt lgkmcnt(" #n ")" ::: "memory")
; template <class Epi, class Sched, bool ALIGN_EPI = false, bool SP2 = false, bool AROWS128 = false>
; __device__ __forceinline__ void gemm_phase(PG8_LAS unsigned char* lds, const Gemm g, const Sched& S, const Epi& E) {
;     ...
;         const bool has_next = S.next(ui + 1, nxt);
;         const char* nA = has_next ? (const char*)g.A + (size_t)nxt.pm * tstep : cA; const char* nB = has_next ? (const char*)g.Bt + (size_t)nxt.pn * tstep : cB;
;         for (int t = 0; t < nt; t += 2) {
;             const bool last = (t == nt - 2);
;             const char* a1 = cA + (size_t)(t + 1) * kstep;
;             const char* a2 = last ? nA : cA + (size_t)(t + 2) * kstep; const char* b2 = last ? nB : cB + (size_t)(t + 2) * kstep;
;             const char* a3 = a2 + kstep; const char* b3 = b2 + kstep;
;             if (last && has_next) S.a_ready(nxt);
;             if constexpr (SP2) {
;             PG8_LDB(B0, 0, 0); PG8_LDB(B1, 0, 1); PG8_SCHED; PG8_LDA(At, 0, 0); PG8_STAGE(PG8_SA(1, 1), a1 + hstepA, voffA);
;             PG8_WAIT_V(8); PG8_WAIT_L(0); PG8_BAR; PG8_MMA(0, 0, At, B0); PG8_MMA(0, 1, At, B1); PG8_BAR; PG8_SCHED;
.LBB0_118:
	s_ashr_i32 s25, s24, 31
	s_lshl_b64 s[26:27], s[24:25], 19
	s_add_u32 s26, s46, s26
	s_addc_u32 s27, s47, s27
	s_and_b64 s[28:29], s[0:1], exec
	s_cselect_b32 s25, s27, s49
	s_cselect_b32 s76, s26, s48
	s_ashr_i32 s15, s14, 31
	s_lshl_b64 s[28:29], s[14:15], 19
	s_add_u32 s28, s82, s28
	s_addc_u32 s29, s83, s29
	s_and_b64 s[58:59], s[0:1], exec
	s_cselect_b32 s15, s29, s51
	s_cselect_b32 s77, s28, s50
	s_add_u32 s48, s48, 0x40080
	s_addc_u32 s49, s49, 0
	s_add_u32 s91, s50, 0x100
	v_mov_b32_e32 v0, 0
	s_addc_u32 s92, s51, 0
	s_mov_b32 s93, -2
	v_mov_b64_e32 v[0:1], 0
	v_mov_b64_e32 v[2:3], 0
	v_mov_b64_e32 v[4:5], 0
	v_mov_b64_e32 v[6:7], 0
	v_mov_b64_e32 v[8:9], 0
	v_mov_b64_e32 v[10:11], 0
	v_mov_b64_e32 v[12:13], 0
	v_mov_b64_e32 v[14:15], 0
	v_mov_b64_e32 v[16:17], 0
	v_mov_b64_e32 v[18:19], 0
	v_mov_b64_e32 v[20:21], 0
	v_mov_b64_e32 v[22:23], 0
	v_mov_b64_e32 v[24:25], 0
	v_mov_b64_e32 v[26:27], 0
	v_mov_b64_e32 v[28:29], 0
	v_mov_b64_e32 v[30:31], 0
	v_mov_b64_e32 v[32:33], 0
	v_mov_b64_e32 v[34:35], 0
	v_mov_b64_e32 v[36:37], 0
	v_mov_b64_e32 v[38:39], 0
	v_mov_b64_e32 v[40:41], 0
	v_mov_b64_e32 v[42:43], 0
	v_mov_b64_e32 v[44:45], 0
	v_mov_b64_e32 v[46:47], 0
	v_mov_b64_e32 v[48:49], 0
	v_mov_b64_e32 v[50:51], 0
	v_mov_b64_e32 v[52:53], 0
	v_mov_b64_e32 v[54:55], 0
	v_mov_b64_e32 v[56:57], 0
	v_mov_b64_e32 v[58:59], 0
	v_mov_b64_e32 v[60:61], 0
	v_mov_b64_e32 v[62:63], 0
	v_mov_b64_e32 v[64:65], 0
	v_mov_b64_e32 v[66:67], 0
	v_mov_b64_e32 v[68:69], 0
	v_mov_b64_e32 v[70:71], 0
	v_mov_b64_e32 v[72:73], 0
	v_mov_b64_e32 v[74:75], 0
	v_mov_b64_e32 v[76:77], 0
	v_mov_b64_e32 v[78:79], 0
	v_mov_b64_e32 v[80:81], 0
	v_mov_b64_e32 v[82:83], 0
	v_mov_b64_e32 v[84:85], 0
	v_mov_b64_e32 v[86:87], 0
	v_mov_b64_e32 v[88:89], 0
	v_mov_b64_e32 v[90:91], 0
	v_mov_b64_e32 v[92:93], 0
	v_mov_b64_e32 v[94:95], 0
	v_mov_b64_e32 v[96:97], 0
	v_mov_b64_e32 v[98:99], 0
	v_mov_b64_e32 v[100:101], 0
	v_mov_b64_e32 v[102:103], 0
	v_mov_b64_e32 v[104:105], 0
	v_mov_b64_e32 v[106:107], 0
	v_mov_b64_e32 v[108:109], 0
	v_mov_b64_e32 v[110:111], 0
	v_mov_b64_e32 v[112:113], 0
	v_mov_b64_e32 v[114:115], 0
	v_mov_b64_e32 v[116:117], 0
	v_mov_b64_e32 v[118:119], 0
	v_mov_b64_e32 v[120:121], 0
	v_mov_b64_e32 v[122:123], 0
	v_mov_b64_e32 v[124:125], 0
	v_mov_b64_e32 v[126:127], 0
	ds_read_b128 v[148:151], v155
	ds_read_b128 v[160:163], v155 offset:1024
	ds_read_b128 v[164:167], v155 offset:2048
	ds_read_b128 v[168:171], v155 offset:3072
	ds_read_b128 v[172:175], v156
	ds_read_b128 v[176:179], v156 offset:1024
	ds_read_b128 v[180:183], v156 offset:2048
	ds_read_b128 v[184:187], v156 offset:3072
	s_add_u32 s50, s48, 0xfffc0080
	s_addc_u32 s51, s49, -1
	s_cmp_eq_u32 s93, 12
	s_cselect_b32 s59, s25, s51
	s_cselect_b32 s58, s76, s50
	s_cselect_b32 s51, s15, s92
	s_cselect_b32 s50, s77, s91
	v_lshl_add_u64 v[208:209], s[48:49], 0, v[138:139]
	s_add_i32 m0, s31, 0xc000
	ds_read_b128 v[188:191], v157
	ds_read_b128 v[192:195], v157 offset:1024
	ds_read_b128 v[196:199], v157 offset:2048
	ds_read_b128 v[200:203], v157 offset:3072
	ds_read_b128 v[204:207], v157 offset:4096
	ds_read_b128 v[212:215], v157 offset:5120
	ds_read_b128 v[216:219], v157 offset:6144
	ds_read_b128 v[220:223], v157 offset:7168
	global_load_lds_dwordx4 v[208:209], off
	v_lshl_add_u64 v[208:209], s[48:49], 0, v[140:141]
	s_add_i32 m0, s31, 0xe000
	s_nop 0
	global_load_lds_dwordx4 v[208:209], off
	s_waitcnt vmcnt(8)
	s_waitcnt lgkmcnt(0)
	s_barrier
	s_setprio 1
	s_waitcnt lgkmcnt(0)
	v_mfma_f32_16x16x32_bf16 v[124:127], v[148:151], v[188:191], 0
	v_mfma_f32_16x16x32_bf16 v[120:123], v[164:167], v[188:191], 0
	v_mfma_f32_16x16x32_bf16 v[112:115], v[148:151], v[196:199], 0
	v_mfma_f32_16x16x32_bf16 v[104:107], v[164:167], v[196:199], 0
	v_mfma_f32_16x16x32_bf16 v[96:99], v[148:151], v[204:207], 0
	v_mfma_f32_16x16x32_bf16 v[88:91], v[164:167], v[204:207], 0
	v_mfma_f32_16x16x32_bf16 v[80:83], v[148:151], v[216:219], 0
	v_mfma_f32_16x16x32_bf16 v[72:75], v[164:167], v[216:219], 0
	v_mfma_f32_16x16x32_bf16 v[124:127], v[160:163], v[192:195], v[124:127]
	v_mfma_f32_16x16x32_bf16 v[120:123], v[168:171], v[192:195], v[120:123]
	v_mfma_f32_16x16x32_bf16 v[112:115], v[160:163], v[200:203], v[112:115]
	v_mfma_f32_16x16x32_bf16 v[104:107], v[168:171], v[200:203], v[104:107]
	v_mfma_f32_16x16x32_bf16 v[96:99], v[160:163], v[212:215], v[96:99]
	v_mfma_f32_16x16x32_bf16 v[88:91], v[168:171], v[212:215], v[88:91]
	v_mfma_f32_16x16x32_bf16 v[80:83], v[160:163], v[220:223], v[80:83]
	v_mfma_f32_16x16x32_bf16 v[72:75], v[168:171], v[220:223], v[72:75]
	s_setprio 0
	s_setprio 1
	v_mfma_f32_16x16x32_bf16 v[116:119], v[172:175], v[188:191], 0
	v_mfma_f32_16x16x32_bf16 v[108:111], v[180:183], v[188:191], 0
	v_mfma_f32_16x16x32_bf16 v[100:103], v[172:175], v[196:199], 0
	v_mfma_f32_16x16x32_bf16 v[92:95], v[180:183], v[196:199], 0
	v_mfma_f32_16x16x32_bf16 v[84:87], v[172:175], v[204:207], 0
	v_mfma_f32_16x16x32_bf16 v[76:79], v[180:183], v[204:207], 0
	v_mfma_f32_16x16x32_bf16 v[68:71], v[172:175], v[216:219], 0
	v_mfma_f32_16x16x32_bf16 v[64:67], v[180:183], v[216:219], 0
	v_mfma_f32_16x16x32_bf16 v[116:119], v[176:179], v[192:195], v[116:119]
	v_mfma_f32_16x16x32_bf16 v[108:111], v[184:187], v[192:195], v[108:111]
	v_mfma_f32_16x16x32_bf16 v[100:103], v[176:179], v[200:203], v[100:103]
	v_mfma_f32_16x16x32_bf16 v[92:95], v[184:187], v[200:203], v[92:95]
	v_mfma_f32_16x16x32_bf16 v[84:87], v[176:179], v[212:215], v[84:87]
	v_mfma_f32_16x16x32_bf16 v[76:79], v[184:187], v[212:215], v[76:79]
	v_mfma_f32_16x16x32_bf16 v[68:71], v[176:179], v[220:223], v[68:71]
	v_mfma_f32_16x16x32_bf16 v[64:67], v[184:187], v[220:223], v[64:67]
	s_setprio 0
	s_barrier
; #define PG8_STAGE(bufoff, gbase, voff) do { _Pragma("unroll") for (int _i = 0; _i < 2; ++_i) \
;         __builtin_amdgcn_global_load_lds((const unsigned*)((const char*)(gbase) + (voff)[_i]), (PG8_LAS unsigned*)(lds + (bufoff) + ldsw + _i * 8192), 16, 0, 0); } while (0)
; #define PG8_LDA(dst, b, h) do { _Pragma("unroll") for (int m = 0; m < 4; ++m) _Pragma("unroll") for (int k = 0; k < 2; ++k) dst[m][k] = *(const PG8_LAS bf16x8*)(lds + PG8_SA(b, h) + aoff + m * 2048 + k * 1024); } while (0)
; #define PG8_LDB(dst, b, h) do { _Pragma("unroll") for (int n = 0; n < 2; ++n) _Pragma("unroll") for (int k = 0; k < 2; ++k) dst[n][k] = *(const PG8_LAS bf16x8*)(lds + PG8_SB(b, h) + boff + n * 2048 + k * 1024); } while (0)
; #define PG8_MMA(ai, bj, At, Bt) do { __builtin_amdgcn_s_setprio(1); _Pragma("unroll") for (int m = 0; m < 4; ++m) _Pragma("unroll") for (int n = 0; n < 2; ++n) _Pragma("unroll") for (int k = 0; k < 2; ++k) \
;         acc[ai][bj][m][n] = __builtin_amdgcn_mfma_f32_16x16x32_bf16(Bt[n][k], At[m][k], acc[ai][bj][m][n], 0, 0, 0); __builtin_amdgcn_s_setprio(0); } while (0)
; #define PG8_WAIT_V(n) asm volatile("s_waitcnt vmcnt(" #n ")" ::: "memory")
; #define PG8_WAIT_L(n) asm volatile("s_waitcnt lgkmcnt(" #n ")" ::: "memory")
; #define PG8_BAR __builtin_amdgcn_s_barrier()
; #define PG8_SCHED __builtin_amdgcn_sched_barrier(0)
; template <class Epi, class Sched, bool ALIGN_EPI = false, bool SP2 = false, bool AROWS128 = false>
; __device__ __forceinline__ void gemm_phase(PG8_LAS unsigned char* lds, const Gemm g, const Sched& S, const Epi& E) {
;     ...
;             PG8_LDA(At, 0, 1); PG8_STAGE(PG8_SB(0, 0), b2, voffB); PG8_STAGE(PG8_SB(0, 1), b2 + hstep, voffB); PG8_STAGE(PG8_SA(0, 0), a2, voffA);
;             PG8_WAIT_V(8); PG8_WAIT_L(0); PG8_BAR; PG8_MMA(1, 0, At, B0); PG8_MMA(1, 1, At, B1); PG8_BAR; PG8_SCHED;
;             PG8_LDB(B0, 1, 0); PG8_LDB(B1, 1, 1); PG8_SCHED; PG8_LDA(At, 1, 0); PG8_STAGE(PG8_SA(0, 1), a2 + hstepA, voffA);
;             PG8_WAIT_V(8); PG8_WAIT_L(0); PG8_BAR; PG8_MMA(0, 0, At, B0); PG8_MMA(0, 1, At, B1); PG8_BAR; PG8_SCHED;
	s_add_i32 s94, s87, s3
	v_lshl_add_u64 v[208:209], s[50:51], 0, v[134:135]
	s_mov_b32 m0, s94
	ds_read_b128 v[188:191], v157 offset:16384
	ds_read_b128 v[192:195], v157 offset:17408
	ds_read_b128 v[196:199], v157 offset:18432
	ds_read_b128 v[200:203], v157 offset:19456
	ds_read_b128 v[204:207], v157 offset:20480
	ds_read_b128 v[212:215], v157 offset:21504
	ds_read_b128 v[216:219], v157 offset:22528
	ds_read_b128 v[220:223], v157 offset:23552
	global_load_lds_dwordx4 v[208:209], off
	s_add_i32 m0, s94, 0x2000
	s_add_u32 s94, s50, 0x40000
	v_lshl_add_u64 v[224:225], s[50:51], 0, v[130:131]
	s_addc_u32 s95, s51, 0
	s_add_i32 s96, s88, s3
	global_load_lds_dwordx4 v[224:225], off
	v_lshl_add_u64 v[226:227], s[94:95], 0, v[134:135]
	s_mov_b32 m0, s96
	v_lshl_add_u64 v[228:229], s[58:59], 0, v[132:133]
	global_load_lds_dwordx4 v[226:227], off
	v_lshl_add_u64 v[226:227], s[94:95], 0, v[130:131]
	s_add_i32 m0, s96, 0x2000
	s_nop 0
	global_load_lds_dwordx4 v[226:227], off
	v_lshl_add_u64 v[226:227], s[58:59], 0, v[136:137]
	s_mov_b32 m0, s31
	s_nop 0
	global_load_lds_dwordx4 v[226:227], off
	s_mov_b32 m0, s64
	s_nop 0
	global_load_lds_dwordx4 v[228:229], off
	s_waitcnt vmcnt(8)
	s_waitcnt lgkmcnt(0)
	s_barrier
	s_setprio 1
	s_waitcnt lgkmcnt(0)
	v_mfma_f32_16x16x32_bf16 v[60:63], v[148:151], v[188:191], 0
	v_mfma_f32_16x16x32_bf16 v[56:59], v[164:167], v[188:191], 0
	v_mfma_f32_16x16x32_bf16 v[48:51], v[148:151], v[196:199], 0
	v_mfma_f32_16x16x32_bf16 v[40:43], v[164:167], v[196:199], 0
	v_mfma_f32_16x16x32_bf16 v[32:35], v[148:151], v[204:207], 0
	v_mfma_f32_16x16x32_bf16 v[24:27], v[164:167], v[204:207], 0
	v_mfma_f32_16x16x32_bf16 v[16:19], v[148:151], v[216:219], 0
	v_mfma_f32_16x16x32_bf16 v[8:11], v[164:167], v[216:219], 0
	v_mfma_f32_16x16x32_bf16 v[60:63], v[160:163], v[192:195], v[60:63]
	v_mfma_f32_16x16x32_bf16 v[56:59], v[168:171], v[192:195], v[56:59]
	v_mfma_f32_16x16x32_bf16 v[48:51], v[160:163], v[200:203], v[48:51]
	v_mfma_f32_16x16x32_bf16 v[40:43], v[168:171], v[200:203], v[40:43]
	v_mfma_f32_16x16x32_bf16 v[32:35], v[160:163], v[212:215], v[32:35]
	v_mfma_f32_16x16x32_bf16 v[24:27], v[168:171], v[212:215], v[24:27]
	v_mfma_f32_16x16x32_bf16 v[16:19], v[160:163], v[220:223], v[16:19]
	v_mfma_f32_16x16x32_bf16 v[8:11], v[168:171], v[220:223], v[8:11]
	s_setprio 0
	s_setprio 1
	v_mfma_f32_16x16x32_bf16 v[52:55], v[172:175], v[188:191], 0
	v_mfma_f32_16x16x32_bf16 v[44:47], v[180:183], v[188:191], 0
	v_mfma_f32_16x16x32_bf16 v[36:39], v[172:175], v[196:199], 0
	v_mfma_f32_16x16x32_bf16 v[28:31], v[180:183], v[196:199], 0
	v_mfma_f32_16x16x32_bf16 v[20:23], v[172:175], v[204:207], 0
	v_mfma_f32_16x16x32_bf16 v[12:15], v[180:183], v[204:207], 0
	v_mfma_f32_16x16x32_bf16 v[4:7], v[172:175], v[216:219], 0
	v_mfma_f32_16x16x32_bf16 v[0:3], v[180:183], v[216:219], 0
	v_mfma_f32_16x16x32_bf16 v[52:55], v[176:179], v[192:195], v[52:55]
	v_mfma_f32_16x16x32_bf16 v[44:47], v[184:187], v[192:195], v[44:47]
	v_mfma_f32_16x16x32_bf16 v[36:39], v[176:179], v[200:203], v[36:39]
	v_mfma_f32_16x16x32_bf16 v[28:31], v[184:187], v[200:203], v[28:31]
	v_mfma_f32_16x16x32_bf16 v[20:23], v[176:179], v[212:215], v[20:23]
	v_mfma_f32_16x16x32_bf16 v[12:15], v[184:187], v[212:215], v[12:15]
	v_mfma_f32_16x16x32_bf16 v[4:7], v[176:179], v[220:223], v[4:7]
	v_mfma_f32_16x16x32_bf16 v[0:3], v[184:187], v[220:223], v[0:3]
	s_setprio 0
	s_barrier
	s_add_i32 s94, 0, 0x18000
	v_add_u32_e32 v146, s94, v153
	s_add_i32 s95, 0, 0x1c000
	ds_read_b128 v[148:151], v146
	ds_read_b128 v[160:163], v146 offset:1024
	ds_read_b128 v[164:167], v146 offset:2048
	ds_read_b128 v[168:171], v146 offset:3072
	v_add_u32_e32 v146, s95, v153
	ds_read_b128 v[172:175], v146
	ds_read_b128 v[176:179], v146 offset:1024
	ds_read_b128 v[180:183], v146 offset:2048
	ds_read_b128 v[184:187], v146 offset:3072
	s_add_u32 s58, s58, 0x40000
	s_addc_u32 s59, s59, 0
	s_mov_b32 m0, s65
	v_lshl_add_u64 v[230:231], s[58:59], 0, v[136:137]
	ds_read_b128 v[188:191], v157 offset:32768
	ds_read_b128 v[192:195], v157 offset:33792
	ds_read_b128 v[196:199], v157 offset:34816
	ds_read_b128 v[200:203], v157 offset:35840
	ds_read_b128 v[204:207], v157 offset:36864
	ds_read_b128 v[212:215], v157 offset:37888
	ds_read_b128 v[216:219], v157 offset:38912
	ds_read_b128 v[220:223], v157 offset:39936
	global_load_lds_dwordx4 v[230:231], off
	v_lshl_add_u64 v[230:231], s[58:59], 0, v[132:133]
	s_mov_b32 m0, s72
	s_nop 0
	global_load_lds_dwordx4 v[230:231], off
	s_waitcnt vmcnt(8)
	s_waitcnt lgkmcnt(0)
	s_barrier
; #define PG8_STAGE(bufoff, gbase, voff) do { _Pragma("unroll") for (int _i = 0; _i < 2; ++_i) \
;         __builtin_amdgcn_global_load_lds((const unsigned*)((const char*)(gbase) + (voff)[_i]), (PG8_LAS unsigned*)(lds + (bufoff) + ldsw + _i * 8192), 16, 0, 0); } while (0)
; #define PG8_LDA(dst, b, h) do { _Pragma("unroll") for (int m = 0; m < 4; ++m) _Pragma("unroll") for (int k = 0; k < 2; ++k) dst[m][k] = *(const PG8_LAS bf16x8*)(lds + PG8_SA(b, h) + aoff + m * 2048 + k * 1024); } while (0)
; #define PG8_MMA(ai, bj, At, Bt) do { __builtin_amdgcn_s_setprio(1); _Pragma("unroll") for (int m = 0; m < 4; ++m) _Pragma("unroll") for (int n = 0; n < 2; ++n) _Pragma("unroll") for (int k = 0; k < 2; ++k) \
;         acc[ai][bj][m][n] = __builtin_amdgcn_mfma_f32_16x16x32_bf16(Bt[n][k], At[m][k], acc[ai][bj][m][n], 0, 0, 0); __builtin_amdgcn_s_setprio(0); } while (0)
; #define PG8_WAIT_V(n) asm volatile("s_waitcnt vmcnt(" #n ")" ::: "memory")
; #define PG8_WAIT_L(n) asm volatile("s_waitcnt lgkmcnt(" #n ")" ::: "memory")
; #define PG8_BAR __builtin_amdgcn_s_barrier()
; #define PG8_SCHED __builtin_amdgcn_sched_barrier(0)
; template <class Epi, class Sched, bool ALIGN_EPI = false, bool SP2 = false, bool AROWS128 = false>
; __device__ __forceinline__ void gemm_phase(PG8_LAS unsigned char* lds, const Gemm g, const Sched& S, const Epi& E) {
;     ...
;             PG8_WAIT_V(8); PG8_WAIT_L(0); PG8_BAR; PG8_MMA(0, 0, At, B0); PG8_MMA(0, 1, At, B1); PG8_BAR; PG8_SCHED;
;             PG8_LDA(At, 1, 1); PG8_STAGE(PG8_SB(1, 0), b3, voffB); PG8_STAGE(PG8_SB(1, 1), b3 + hstep, voffB); PG8_STAGE(PG8_SA(1, 0), a3, voffA);
;             PG8_WAIT_V(8); PG8_WAIT_L(0); PG8_BAR; PG8_MMA(1, 0, At, B0); PG8_MMA(1, 1, At, B1); PG8_BAR; PG8_SCHED;
	s_setprio 1
	s_waitcnt lgkmcnt(0)
	v_mfma_f32_16x16x32_bf16 v[124:127], v[148:151], v[188:191], v[124:127]
	v_mfma_f32_16x16x32_bf16 v[120:123], v[164:167], v[188:191], v[120:123]
	v_mfma_f32_16x16x32_bf16 v[112:115], v[148:151], v[196:199], v[112:115]
	v_mfma_f32_16x16x32_bf16 v[104:107], v[164:167], v[196:199], v[104:107]
	v_mfma_f32_16x16x32_bf16 v[96:99], v[148:151], v[204:207], v[96:99]
	v_mfma_f32_16x16x32_bf16 v[88:91], v[164:167], v[204:207], v[88:91]
	v_mfma_f32_16x16x32_bf16 v[80:83], v[148:151], v[216:219], v[80:83]
	v_mfma_f32_16x16x32_bf16 v[72:75], v[164:167], v[216:219], v[72:75]
	v_mfma_f32_16x16x32_bf16 v[124:127], v[160:163], v[192:195], v[124:127]
	v_mfma_f32_16x16x32_bf16 v[120:123], v[168:171], v[192:195], v[120:123]
	v_mfma_f32_16x16x32_bf16 v[112:115], v[160:163], v[200:203], v[112:115]
	v_mfma_f32_16x16x32_bf16 v[104:107], v[168:171], v[200:203], v[104:107]
	v_mfma_f32_16x16x32_bf16 v[96:99], v[160:163], v[212:215], v[96:99]
	v_mfma_f32_16x16x32_bf16 v[88:91], v[168:171], v[212:215], v[88:91]
	v_mfma_f32_16x16x32_bf16 v[80:83], v[160:163], v[220:223], v[80:83]
	v_mfma_f32_16x16x32_bf16 v[72:75], v[168:171], v[220:223], v[72:75]
	s_setprio 0
	s_setprio 1
	v_mfma_f32_16x16x32_bf16 v[116:119], v[172:175], v[188:191], v[116:119]
	v_mfma_f32_16x16x32_bf16 v[108:111], v[180:183], v[188:191], v[108:111]
	v_mfma_f32_16x16x32_bf16 v[100:103], v[172:175], v[196:199], v[100:103]
	v_mfma_f32_16x16x32_bf16 v[92:95], v[180:183], v[196:199], v[92:95]
	v_mfma_f32_16x16x32_bf16 v[84:87], v[172:175], v[204:207], v[84:87]
	v_mfma_f32_16x16x32_bf16 v[76:79], v[180:183], v[204:207], v[76:79]
	v_mfma_f32_16x16x32_bf16 v[68:71], v[172:175], v[216:219], v[68:71]
	v_mfma_f32_16x16x32_bf16 v[64:67], v[180:183], v[216:219], v[64:67]
	v_mfma_f32_16x16x32_bf16 v[116:119], v[176:179], v[192:195], v[116:119]
	v_mfma_f32_16x16x32_bf16 v[108:111], v[184:187], v[192:195], v[108:111]
	v_mfma_f32_16x16x32_bf16 v[100:103], v[176:179], v[200:203], v[100:103]
	v_mfma_f32_16x16x32_bf16 v[92:95], v[184:187], v[200:203], v[92:95]
	v_mfma_f32_16x16x32_bf16 v[84:87], v[176:179], v[212:215], v[84:87]
	v_mfma_f32_16x16x32_bf16 v[76:79], v[184:187], v[212:215], v[76:79]
	v_mfma_f32_16x16x32_bf16 v[68:71], v[176:179], v[220:223], v[68:71]
	v_mfma_f32_16x16x32_bf16 v[64:67], v[184:187], v[220:223], v[64:67]
	s_setprio 0
	s_barrier
	s_add_i32 s58, s94, s3
	v_lshl_add_u64 v[208:209], v[208:209], 0, s[6:7]
	s_mov_b32 m0, s58
	ds_read_b128 v[188:191], v157 offset:49152
	ds_read_b128 v[192:195], v157 offset:50176
	ds_read_b128 v[196:199], v157 offset:51200
	ds_read_b128 v[200:203], v157 offset:52224
	ds_read_b128 v[204:207], v157 offset:53248
	ds_read_b128 v[212:215], v157 offset:54272
	ds_read_b128 v[216:219], v157 offset:55296
	ds_read_b128 v[220:223], v157 offset:56320
	global_load_lds_dwordx4 v[208:209], off
	s_add_i32 m0, s58, 0x2000
	s_add_u32 s50, s50, 0x40080
	v_lshl_add_u64 v[208:209], v[224:225], 0, s[6:7]
	s_addc_u32 s51, s51, 0
	s_add_i32 s58, s95, s3
	global_load_lds_dwordx4 v[208:209], off
	v_lshl_add_u64 v[208:209], s[50:51], 0, v[134:135]
	s_mov_b32 m0, s58
	s_nop 0
	global_load_lds_dwordx4 v[208:209], off
	v_lshl_add_u64 v[208:209], s[50:51], 0, v[130:131]
	s_add_i32 m0, s58, 0x2000
	s_nop 0
	global_load_lds_dwordx4 v[208:209], off
	v_lshl_add_u64 v[208:209], v[226:227], 0, s[6:7]
	s_mov_b32 m0, s81
	s_nop 0
	global_load_lds_dwordx4 v[208:209], off
	v_lshl_add_u64 v[208:209], v[228:229], 0, s[6:7]
	s_mov_b32 m0, s84
	s_nop 0
	global_load_lds_dwordx4 v[208:209], off
	s_waitcnt vmcnt(8)
	s_waitcnt lgkmcnt(0)
	s_barrier
	s_setprio 1
	s_waitcnt lgkmcnt(0)
	v_mfma_f32_16x16x32_bf16 v[60:63], v[148:151], v[188:191], v[60:63]
	v_mfma_f32_16x16x32_bf16 v[56:59], v[164:167], v[188:191], v[56:59]
	v_mfma_f32_16x16x32_bf16 v[48:51], v[148:151], v[196:199], v[48:51]
	v_mfma_f32_16x16x32_bf16 v[40:43], v[164:167], v[196:199], v[40:43]
	v_mfma_f32_16x16x32_bf16 v[32:35], v[148:151], v[204:207], v[32:35]
	v_mfma_f32_16x16x32_bf16 v[24:27], v[164:167], v[204:207], v[24:27]
	v_mfma_f32_16x16x32_bf16 v[16:19], v[148:151], v[216:219], v[16:19]
	v_mfma_f32_16x16x32_bf16 v[8:11], v[164:167], v[216:219], v[8:11]
	v_mfma_f32_16x16x32_bf16 v[60:63], v[160:163], v[192:195], v[60:63]
	v_mfma_f32_16x16x32_bf16 v[56:59], v[168:171], v[192:195], v[56:59]
	v_mfma_f32_16x16x32_bf16 v[48:51], v[160:163], v[200:203], v[48:51]
	v_mfma_f32_16x16x32_bf16 v[40:43], v[168:171], v[200:203], v[40:43]
	v_mfma_f32_16x16x32_bf16 v[32:35], v[160:163], v[212:215], v[32:35]
	v_mfma_f32_16x16x32_bf16 v[24:27], v[168:171], v[212:215], v[24:27]
	v_mfma_f32_16x16x32_bf16 v[16:19], v[160:163], v[220:223], v[16:19]
	v_mfma_f32_16x16x32_bf16 v[8:11], v[168:171], v[220:223], v[8:11]
	s_setprio 0
	s_setprio 1
	v_mfma_f32_16x16x32_bf16 v[52:55], v[172:175], v[188:191], v[52:55]
	v_mfma_f32_16x16x32_bf16 v[44:47], v[180:183], v[188:191], v[44:47]
	v_mfma_f32_16x16x32_bf16 v[36:39], v[172:175], v[196:199], v[36:39]
	v_mfma_f32_16x16x32_bf16 v[28:31], v[180:183], v[196:199], v[28:31]
	v_mfma_f32_16x16x32_bf16 v[20:23], v[172:175], v[204:207], v[20:23]
	v_mfma_f32_16x16x32_bf16 v[12:15], v[180:183], v[204:207], v[12:15]
	v_mfma_f32_16x16x32_bf16 v[4:7], v[172:175], v[216:219], v[4:7]
	v_mfma_f32_16x16x32_bf16 v[0:3], v[180:183], v[216:219], v[0:3]
	v_mfma_f32_16x16x32_bf16 v[52:55], v[176:179], v[192:195], v[52:55]
	v_mfma_f32_16x16x32_bf16 v[44:47], v[184:187], v[192:195], v[44:47]
	v_mfma_f32_16x16x32_bf16 v[36:39], v[176:179], v[200:203], v[36:39]
	v_mfma_f32_16x16x32_bf16 v[28:31], v[184:187], v[200:203], v[28:31]
	v_mfma_f32_16x16x32_bf16 v[20:23], v[176:179], v[212:215], v[20:23]
	v_mfma_f32_16x16x32_bf16 v[12:15], v[184:187], v[212:215], v[12:15]
	v_mfma_f32_16x16x32_bf16 v[4:7], v[176:179], v[220:223], v[4:7]
	v_mfma_f32_16x16x32_bf16 v[0:3], v[184:187], v[220:223], v[0:3]
	s_setprio 0
	s_barrier
	s_add_i32 s93, s93, 2
	s_add_u32 s48, s48, 0x100
	s_addc_u32 s49, s49, 0
	s_add_u32 s91, s91, 0x100
	s_addc_u32 s92, s92, 0
	s_cmp_gt_u32 s93, 13
	s_cbranch_scc0 .LBB0_119
	s_nop 0

; #define PG8_STAGE(bufoff, gbase, voff) do { _Pragma("unroll") for (int _i = 0; _i < 2; ++_i) \
;         __builtin_amdgcn_global_load_lds((const unsigned*)((const char*)(gbase) + (voff)[_i]), (PG8_LAS unsigned*)(lds + (bufoff) + ldsw + _i * 8192), 16, 0, 0); } while (0)
; #define PG8_LDA(dst, b, h) do { _Pragma("unroll") for (int m = 0; m < 4; ++m) _Pragma("unroll") for (int k = 0; k < 2; ++k) dst[m][k] = *(const PG8_LAS bf16x8*)(lds + PG8_SA(b, h) + aoff + m * 2048 + k * 1024); } while (0)
; #define PG8_LDB(dst, b, h) do { _Pragma("unroll") for (int n = 0; n < 2; ++n) _Pragma("unroll") for (int k = 0; k < 2; ++k) dst[n][k] = *(const PG8_LAS bf16x8*)(lds + PG8_SB(b, h) + boff + n * 2048 + k * 1024); } while (0)
; #define PG8_MMA(ai, bj, At, Bt) do { __builtin_amdgcn_s_setprio(1); _Pragma("unroll") for (int m = 0; m < 4; ++m) _Pragma("unroll") for (int n = 0; n < 2; ++n) _Pragma("unroll") for (int k = 0; k < 2; ++k) \
;         acc[ai][bj][m][n] = __builtin_amdgcn_mfma_f32_16x16x32_bf16(Bt[n][k], At[m][k], acc[ai][bj][m][n], 0, 0, 0); __builtin_amdgcn_s_setprio(0); } while (0)
; #define PG8_WAIT_V(n) asm volatile("s_waitcnt vmcnt(" #n ")" ::: "memory")
; #define PG8_WAIT_L(n) asm volatile("s_waitcnt lgkmcnt(" #n ")" ::: "memory")
; template <class Epi, class Sched, bool ALIGN_EPI = false, bool SP2 = false, bool AROWS128 = false>
; __device__ __forceinline__ void gemm_phase(PG8_LAS unsigned char* lds, const Gemm g, const Sched& S, const Epi& E) {
;     ...
;         const bool has_next = S.next(ui + 1, nxt);
;         const char* nA = has_next ? (const char*)g.A + (size_t)nxt.pm * tstep : cA; const char* nB = has_next ? (const char*)g.Bt + (size_t)nxt.pn * tstep : cB;
;         for (int t = 0; t < nt; t += 2) {
;             const bool last = (t == nt - 2);
;             const char* a1 = cA + (size_t)(t + 1) * kstep;
;             const char* a2 = last ? nA : cA + (size_t)(t + 2) * kstep; const char* b2 = last ? nB : cB + (size_t)(t + 2) * kstep;
;             const char* a3 = a2 + kstep; const char* b3 = b2 + kstep;
;             if (last && has_next) S.a_ready(nxt);
;             if constexpr (SP2) {
;             PG8_LDB(B0, 0, 0); PG8_LDB(B1, 0, 1); PG8_SCHED; PG8_LDA(At, 0, 0); PG8_STAGE(PG8_SA(1, 1), a1 + hstepA, voffA);
;             PG8_WAIT_V(8); PG8_WAIT_L(0); PG8_BAR; PG8_MMA(0, 0, At, B0); PG8_MMA(0, 1, At, B1); PG8_BAR; PG8_SCHED;
.LBB0_488:
	s_ashr_i32 s15, s14, 31
	s_lshl_b64 s[16:17], s[14:15], 19
	s_add_u32 s16, s46, s16
	s_addc_u32 s17, s47, s17
	s_and_b64 s[18:19], s[0:1], exec
	s_cselect_b32 s15, s17, s27
	s_cselect_b32 s76, s16, s26
	s_ashr_i32 s13, s12, 31
	s_lshl_b64 s[18:19], s[12:13], 19
	s_add_u32 s18, s20, s18
	s_addc_u32 s19, s21, s19
	s_and_b64 s[30:31], s[0:1], exec
	s_cselect_b32 s13, s19, s29
	s_cselect_b32 s77, s18, s28
	s_add_u32 s26, s26, 0x40080
	s_addc_u32 s27, s27, 0
	s_add_u32 s82, s28, 0x100
	v_mov_b32_e32 v0, 0
	s_addc_u32 s83, s29, 0
	s_mov_b32 s84, -2
	v_mov_b64_e32 v[0:1], 0
	v_mov_b64_e32 v[2:3], 0
	v_mov_b64_e32 v[4:5], 0
	v_mov_b64_e32 v[6:7], 0
	v_mov_b64_e32 v[8:9], 0
	v_mov_b64_e32 v[10:11], 0
	v_mov_b64_e32 v[12:13], 0
	v_mov_b64_e32 v[14:15], 0
	v_mov_b64_e32 v[16:17], 0
	v_mov_b64_e32 v[18:19], 0
	v_mov_b64_e32 v[20:21], 0
	v_mov_b64_e32 v[22:23], 0
	v_mov_b64_e32 v[24:25], 0
	v_mov_b64_e32 v[26:27], 0
	v_mov_b64_e32 v[28:29], 0
	v_mov_b64_e32 v[30:31], 0
	v_mov_b64_e32 v[32:33], 0
	v_mov_b64_e32 v[34:35], 0
	v_mov_b64_e32 v[36:37], 0
	v_mov_b64_e32 v[38:39], 0
	v_mov_b64_e32 v[40:41], 0
	v_mov_b64_e32 v[42:43], 0
	v_mov_b64_e32 v[44:45], 0
	v_mov_b64_e32 v[46:47], 0
	v_mov_b64_e32 v[48:49], 0
	v_mov_b64_e32 v[50:51], 0
	v_mov_b64_e32 v[52:53], 0
	v_mov_b64_e32 v[54:55], 0
	v_mov_b64_e32 v[56:57], 0
	v_mov_b64_e32 v[58:59], 0
	v_mov_b64_e32 v[60:61], 0
	v_mov_b64_e32 v[62:63], 0
	v_mov_b64_e32 v[64:65], 0
	v_mov_b64_e32 v[66:67], 0
	v_mov_b64_e32 v[68:69], 0
	v_mov_b64_e32 v[70:71], 0
	v_mov_b64_e32 v[72:73], 0
	v_mov_b64_e32 v[74:75], 0
	v_mov_b64_e32 v[76:77], 0
	v_mov_b64_e32 v[78:79], 0
	v_mov_b64_e32 v[80:81], 0
	v_mov_b64_e32 v[82:83], 0
	v_mov_b64_e32 v[84:85], 0
	v_mov_b64_e32 v[86:87], 0
	v_mov_b64_e32 v[88:89], 0
	v_mov_b64_e32 v[90:91], 0
	v_mov_b64_e32 v[92:93], 0
	v_mov_b64_e32 v[94:95], 0
	v_mov_b64_e32 v[96:97], 0
	v_mov_b64_e32 v[98:99], 0
	v_mov_b64_e32 v[100:101], 0
	v_mov_b64_e32 v[102:103], 0
	v_mov_b64_e32 v[104:105], 0
	v_mov_b64_e32 v[106:107], 0
	v_mov_b64_e32 v[108:109], 0
	v_mov_b64_e32 v[110:111], 0
	v_mov_b64_e32 v[112:113], 0
	v_mov_b64_e32 v[114:115], 0
	v_mov_b64_e32 v[116:117], 0
	v_mov_b64_e32 v[118:119], 0
	v_mov_b64_e32 v[120:121], 0
	v_mov_b64_e32 v[122:123], 0
	v_mov_b64_e32 v[124:125], 0
	v_mov_b64_e32 v[126:127], 0
	ds_read_b128 v[152:155], v149
	ds_read_b128 v[156:159], v149 offset:1024
	ds_read_b128 v[160:163], v149 offset:2048
	ds_read_b128 v[164:167], v149 offset:3072
	ds_read_b128 v[168:171], v150
	ds_read_b128 v[172:175], v150 offset:1024
	ds_read_b128 v[176:179], v150 offset:2048
	ds_read_b128 v[180:183], v150 offset:3072
	s_add_u32 s28, s26, 0xfffc0080
	s_addc_u32 s29, s27, -1
	s_cmp_eq_u32 s84, 12
	s_cselect_b32 s31, s15, s29
	s_cselect_b32 s30, s76, s28
	s_cselect_b32 s29, s13, s83
	s_cselect_b32 s28, s77, s82
	v_lshl_add_u64 v[144:145], s[26:27], 0, v[136:137]
	s_add_i32 m0, s25, 0xc000
	ds_read_b128 v[184:187], v151
	ds_read_b128 v[188:191], v151 offset:1024
	ds_read_b128 v[192:195], v151 offset:2048
	ds_read_b128 v[196:199], v151 offset:3072
	ds_read_b128 v[200:203], v151 offset:4096
	ds_read_b128 v[204:207], v151 offset:5120
	ds_read_b128 v[212:215], v151 offset:6144
	ds_read_b128 v[216:219], v151 offset:7168
	global_load_lds_dwordx4 v[144:145], off
	v_lshl_add_u64 v[144:145], s[26:27], 0, v[138:139]
	s_add_i32 m0, s25, 0xe000
	s_nop 0
	global_load_lds_dwordx4 v[144:145], off
	s_waitcnt vmcnt(8)
	s_waitcnt lgkmcnt(0)
	s_barrier
	s_setprio 1
	s_waitcnt lgkmcnt(0)
	v_mfma_f32_16x16x32_bf16 v[124:127], v[152:155], v[184:187], 0
	v_mfma_f32_16x16x32_bf16 v[120:123], v[160:163], v[184:187], 0
	v_mfma_f32_16x16x32_bf16 v[116:119], v[152:155], v[192:195], 0
	v_mfma_f32_16x16x32_bf16 v[108:111], v[160:163], v[192:195], 0
	v_mfma_f32_16x16x32_bf16 v[100:103], v[152:155], v[200:203], 0
	v_mfma_f32_16x16x32_bf16 v[92:95], v[160:163], v[200:203], 0
	v_mfma_f32_16x16x32_bf16 v[84:87], v[152:155], v[212:215], 0
	v_mfma_f32_16x16x32_bf16 v[76:79], v[160:163], v[212:215], 0
	v_mfma_f32_16x16x32_bf16 v[124:127], v[156:159], v[188:191], v[124:127]
	v_mfma_f32_16x16x32_bf16 v[120:123], v[164:167], v[188:191], v[120:123]
	v_mfma_f32_16x16x32_bf16 v[116:119], v[156:159], v[196:199], v[116:119]
	v_mfma_f32_16x16x32_bf16 v[108:111], v[164:167], v[196:199], v[108:111]
	v_mfma_f32_16x16x32_bf16 v[100:103], v[156:159], v[204:207], v[100:103]
	v_mfma_f32_16x16x32_bf16 v[92:95], v[164:167], v[204:207], v[92:95]
	v_mfma_f32_16x16x32_bf16 v[84:87], v[156:159], v[216:219], v[84:87]
	v_mfma_f32_16x16x32_bf16 v[76:79], v[164:167], v[216:219], v[76:79]
	s_setprio 0
	s_setprio 1
	v_mfma_f32_16x16x32_bf16 v[112:115], v[168:171], v[184:187], 0
	v_mfma_f32_16x16x32_bf16 v[104:107], v[176:179], v[184:187], 0
	v_mfma_f32_16x16x32_bf16 v[96:99], v[168:171], v[192:195], 0
	v_mfma_f32_16x16x32_bf16 v[88:91], v[176:179], v[192:195], 0
	v_mfma_f32_16x16x32_bf16 v[80:83], v[168:171], v[200:203], 0
	v_mfma_f32_16x16x32_bf16 v[72:75], v[176:179], v[200:203], 0
	v_mfma_f32_16x16x32_bf16 v[68:71], v[168:171], v[212:215], 0
	v_mfma_f32_16x16x32_bf16 v[64:67], v[176:179], v[212:215], 0
	v_mfma_f32_16x16x32_bf16 v[112:115], v[172:175], v[188:191], v[112:115]
	v_mfma_f32_16x16x32_bf16 v[104:107], v[180:183], v[188:191], v[104:107]
	v_mfma_f32_16x16x32_bf16 v[96:99], v[172:175], v[196:199], v[96:99]
	v_mfma_f32_16x16x32_bf16 v[88:91], v[180:183], v[196:199], v[88:91]
	v_mfma_f32_16x16x32_bf16 v[80:83], v[172:175], v[204:207], v[80:83]
	v_mfma_f32_16x16x32_bf16 v[72:75], v[180:183], v[204:207], v[72:75]
	v_mfma_f32_16x16x32_bf16 v[68:71], v[172:175], v[216:219], v[68:71]
	v_mfma_f32_16x16x32_bf16 v[64:67], v[180:183], v[216:219], v[64:67]
	s_setprio 0
	s_barrier
; #define PG8_STAGE(bufoff, gbase, voff) do { _Pragma("unroll") for (int _i = 0; _i < 2; ++_i) \
;         __builtin_amdgcn_global_load_lds((const unsigned*)((const char*)(gbase) + (voff)[_i]), (PG8_LAS unsigned*)(lds + (bufoff) + ldsw + _i * 8192), 16, 0, 0); } while (0)
; #define PG8_LDA(dst, b, h) do { _Pragma("unroll") for (int m = 0; m < 4; ++m) _Pragma("unroll") for (int k = 0; k < 2; ++k) dst[m][k] = *(const PG8_LAS bf16x8*)(lds + PG8_SA(b, h) + aoff + m * 2048 + k * 1024); } while (0)
; #define PG8_LDB(dst, b, h) do { _Pragma("unroll") for (int n = 0; n < 2; ++n) _Pragma("unroll") for (int k = 0; k < 2; ++k) dst[n][k] = *(const PG8_LAS bf16x8*)(lds + PG8_SB(b, h) + boff + n * 2048 + k * 1024); } while (0)
; #define PG8_MMA(ai, bj, At, Bt) do { __builtin_amdgcn_s_setprio(1); _Pragma("unroll") for (int m = 0; m < 4; ++m) _Pragma("unroll") for (int n = 0; n < 2; ++n) _Pragma("unroll") for (int k = 0; k < 2; ++k) \
;         acc[ai][bj][m][n] = __builtin_amdgcn_mfma_f32_16x16x32_bf16(Bt[n][k], At[m][k], acc[ai][bj][m][n], 0, 0, 0); __builtin_amdgcn_s_setprio(0); } while (0)
; #define PG8_WAIT_V(n) asm volatile("s_waitcnt vmcnt(" #n ")" ::: "memory")
; #define PG8_WAIT_L(n) asm volatile("s_waitcnt lgkmcnt(" #n ")" ::: "memory")
; #define PG8_BAR __builtin_amdgcn_s_barrier()
; #define PG8_SCHED __builtin_amdgcn_sched_barrier(0)
; template <class Epi, class Sched, bool ALIGN_EPI = false, bool SP2 = false, bool AROWS128 = false>
; __device__ __forceinline__ void gemm_phase(PG8_LAS unsigned char* lds, const Gemm g, const Sched& S, const Epi& E) {
;     ...
;             PG8_LDA(At, 0, 1); PG8_STAGE(PG8_SB(0, 0), b2, voffB); PG8_STAGE(PG8_SB(0, 1), b2 + hstep, voffB); PG8_STAGE(PG8_SA(0, 0), a2, voffA);
;             PG8_WAIT_V(8); PG8_WAIT_L(0); PG8_BAR; PG8_MMA(1, 0, At, B0); PG8_MMA(1, 1, At, B1); PG8_BAR; PG8_SCHED;
;             PG8_LDB(B0, 1, 0); PG8_LDB(B1, 1, 1); PG8_SCHED; PG8_LDA(At, 1, 0); PG8_STAGE(PG8_SA(0, 1), a2 + hstepA, voffA);
;             PG8_WAIT_V(8); PG8_WAIT_L(0); PG8_BAR; PG8_MMA(0, 0, At, B0); PG8_MMA(0, 1, At, B1); PG8_BAR; PG8_SCHED;
	s_add_i32 s85, s72, s3
	v_lshl_add_u64 v[144:145], s[28:29], 0, v[132:133]
	s_mov_b32 m0, s85
	ds_read_b128 v[184:187], v151 offset:16384
	ds_read_b128 v[188:191], v151 offset:17408
	ds_read_b128 v[192:195], v151 offset:18432
	ds_read_b128 v[196:199], v151 offset:19456
	ds_read_b128 v[200:203], v151 offset:20480
	ds_read_b128 v[204:207], v151 offset:21504
	ds_read_b128 v[212:215], v151 offset:22528
	ds_read_b128 v[216:219], v151 offset:23552
	global_load_lds_dwordx4 v[144:145], off
	s_add_i32 m0, s85, 0x2000
	s_add_u32 s86, s28, 0x40000
	v_lshl_add_u64 v[208:209], s[28:29], 0, v[128:129]
	s_addc_u32 s87, s29, 0
	s_add_i32 s85, s73, s3
	global_load_lds_dwordx4 v[208:209], off
	v_lshl_add_u64 v[220:221], s[86:87], 0, v[132:133]
	s_mov_b32 m0, s85
	v_lshl_add_u64 v[222:223], s[30:31], 0, v[130:131]
	global_load_lds_dwordx4 v[220:221], off
	v_lshl_add_u64 v[220:221], s[86:87], 0, v[128:129]
	s_add_i32 m0, s85, 0x2000
	s_nop 0
	global_load_lds_dwordx4 v[220:221], off
	v_lshl_add_u64 v[220:221], s[30:31], 0, v[134:135]
	s_mov_b32 m0, s25
	s_nop 0
	global_load_lds_dwordx4 v[220:221], off
	s_mov_b32 m0, s50
	s_nop 0
	global_load_lds_dwordx4 v[222:223], off
	s_waitcnt vmcnt(8)
	s_waitcnt lgkmcnt(0)
	s_barrier
	s_setprio 1
	s_waitcnt lgkmcnt(0)
	v_mfma_f32_16x16x32_bf16 v[60:63], v[152:155], v[184:187], 0
	v_mfma_f32_16x16x32_bf16 v[56:59], v[160:163], v[184:187], 0
	v_mfma_f32_16x16x32_bf16 v[52:55], v[152:155], v[192:195], 0
	v_mfma_f32_16x16x32_bf16 v[44:47], v[160:163], v[192:195], 0
	v_mfma_f32_16x16x32_bf16 v[36:39], v[152:155], v[200:203], 0
	v_mfma_f32_16x16x32_bf16 v[28:31], v[160:163], v[200:203], 0
	v_mfma_f32_16x16x32_bf16 v[20:23], v[152:155], v[212:215], 0
	v_mfma_f32_16x16x32_bf16 v[12:15], v[160:163], v[212:215], 0
	v_mfma_f32_16x16x32_bf16 v[60:63], v[156:159], v[188:191], v[60:63]
	v_mfma_f32_16x16x32_bf16 v[56:59], v[164:167], v[188:191], v[56:59]
	v_mfma_f32_16x16x32_bf16 v[52:55], v[156:159], v[196:199], v[52:55]
	v_mfma_f32_16x16x32_bf16 v[44:47], v[164:167], v[196:199], v[44:47]
	v_mfma_f32_16x16x32_bf16 v[36:39], v[156:159], v[204:207], v[36:39]
	v_mfma_f32_16x16x32_bf16 v[28:31], v[164:167], v[204:207], v[28:31]
	v_mfma_f32_16x16x32_bf16 v[20:23], v[156:159], v[216:219], v[20:23]
	v_mfma_f32_16x16x32_bf16 v[12:15], v[164:167], v[216:219], v[12:15]
	s_setprio 0
	s_setprio 1
	v_mfma_f32_16x16x32_bf16 v[48:51], v[168:171], v[184:187], 0
	v_mfma_f32_16x16x32_bf16 v[40:43], v[176:179], v[184:187], 0
	v_mfma_f32_16x16x32_bf16 v[32:35], v[168:171], v[192:195], 0
	v_mfma_f32_16x16x32_bf16 v[24:27], v[176:179], v[192:195], 0
	v_mfma_f32_16x16x32_bf16 v[16:19], v[168:171], v[200:203], 0
	v_mfma_f32_16x16x32_bf16 v[8:11], v[176:179], v[200:203], 0
	v_mfma_f32_16x16x32_bf16 v[4:7], v[168:171], v[212:215], 0
	v_mfma_f32_16x16x32_bf16 v[0:3], v[176:179], v[212:215], 0
	v_mfma_f32_16x16x32_bf16 v[48:51], v[172:175], v[188:191], v[48:51]
	v_mfma_f32_16x16x32_bf16 v[40:43], v[180:183], v[188:191], v[40:43]
	v_mfma_f32_16x16x32_bf16 v[32:35], v[172:175], v[196:199], v[32:35]
	v_mfma_f32_16x16x32_bf16 v[24:27], v[180:183], v[196:199], v[24:27]
	v_mfma_f32_16x16x32_bf16 v[16:19], v[172:175], v[204:207], v[16:19]
	v_mfma_f32_16x16x32_bf16 v[8:11], v[180:183], v[204:207], v[8:11]
	v_mfma_f32_16x16x32_bf16 v[4:7], v[172:175], v[216:219], v[4:7]
	v_mfma_f32_16x16x32_bf16 v[0:3], v[180:183], v[216:219], v[0:3]
	s_setprio 0
	s_barrier
	s_add_i32 s85, 0, 0x18000
	s_add_i32 s86, 0, 0x1c000
	v_add_u32_e32 v164, s85, v147
	v_add_u32_e32 v180, s86, v147
	ds_read_b128 v[152:155], v164
	ds_read_b128 v[156:159], v164 offset:1024
	ds_read_b128 v[160:163], v164 offset:2048
	ds_read_b128 v[164:167], v164 offset:3072
	ds_read_b128 v[168:171], v180
	ds_read_b128 v[172:175], v180 offset:1024
	ds_read_b128 v[176:179], v180 offset:2048
	ds_read_b128 v[180:183], v180 offset:3072
	s_add_u32 s30, s30, 0x40000
	s_addc_u32 s31, s31, 0
	s_mov_b32 m0, s51
	v_lshl_add_u64 v[224:225], s[30:31], 0, v[134:135]
	ds_read_b128 v[184:187], v151 offset:32768
	ds_read_b128 v[188:191], v151 offset:33792
	ds_read_b128 v[192:195], v151 offset:34816
	ds_read_b128 v[196:199], v151 offset:35840
	ds_read_b128 v[200:203], v151 offset:36864
	ds_read_b128 v[204:207], v151 offset:37888
	ds_read_b128 v[212:215], v151 offset:38912
	ds_read_b128 v[216:219], v151 offset:39936
	global_load_lds_dwordx4 v[224:225], off
	v_lshl_add_u64 v[224:225], s[30:31], 0, v[130:131]
	s_mov_b32 m0, s52
	s_nop 0
	global_load_lds_dwordx4 v[224:225], off
	s_waitcnt vmcnt(8)
	s_waitcnt lgkmcnt(0)
	s_barrier
; #define PG8_STAGE(bufoff, gbase, voff) do { _Pragma("unroll") for (int _i = 0; _i < 2; ++_i) \
;         __builtin_amdgcn_global_load_lds((const unsigned*)((const char*)(gbase) + (voff)[_i]), (PG8_LAS unsigned*)(lds + (bufoff) + ldsw + _i * 8192), 16, 0, 0); } while (0)
; #define PG8_LDA(dst, b, h) do { _Pragma("unroll") for (int m = 0; m < 4; ++m) _Pragma("unroll") for (int k = 0; k < 2; ++k) dst[m][k] = *(const PG8_LAS bf16x8*)(lds + PG8_SA(b, h) + aoff + m * 2048 + k * 1024); } while (0)
; #define PG8_MMA(ai, bj, At, Bt) do { __builtin_amdgcn_s_setprio(1); _Pragma("unroll") for (int m = 0; m < 4; ++m) _Pragma("unroll") for (int n = 0; n < 2; ++n) _Pragma("unroll") for (int k = 0; k < 2; ++k) \
;         acc[ai][bj][m][n] = __builtin_amdgcn_mfma_f32_16x16x32_bf16(Bt[n][k], At[m][k], acc[ai][bj][m][n], 0, 0, 0); __builtin_amdgcn_s_setprio(0); } while (0)
; #define PG8_WAIT_V(n) asm volatile("s_waitcnt vmcnt(" #n ")" ::: "memory")
; #define PG8_WAIT_L(n) asm volatile("s_waitcnt lgkmcnt(" #n ")" ::: "memory")
; #define PG8_BAR __builtin_amdgcn_s_barrier()
; #define PG8_SCHED __builtin_amdgcn_sched_barrier(0)
; template <class Epi, class Sched, bool ALIGN_EPI = false, bool SP2 = false, bool AROWS128 = false>
; __device__ __forceinline__ void gemm_phase(PG8_LAS unsigned char* lds, const Gemm g, const Sched& S, const Epi& E) {
;     ...
;             PG8_WAIT_V(8); PG8_WAIT_L(0); PG8_BAR; PG8_MMA(0, 0, At, B0); PG8_MMA(0, 1, At, B1); PG8_BAR; PG8_SCHED;
;             PG8_LDA(At, 1, 1); PG8_STAGE(PG8_SB(1, 0), b3, voffB); PG8_STAGE(PG8_SB(1, 1), b3 + hstep, voffB); PG8_STAGE(PG8_SA(1, 0), a3, voffA);
;             PG8_WAIT_V(8); PG8_WAIT_L(0); PG8_BAR; PG8_MMA(1, 0, At, B0); PG8_MMA(1, 1, At, B1); PG8_BAR; PG8_SCHED;
	s_setprio 1
	s_waitcnt lgkmcnt(0)
	v_mfma_f32_16x16x32_bf16 v[124:127], v[152:155], v[184:187], v[124:127]
	v_mfma_f32_16x16x32_bf16 v[120:123], v[160:163], v[184:187], v[120:123]
	v_mfma_f32_16x16x32_bf16 v[116:119], v[152:155], v[192:195], v[116:119]
	v_mfma_f32_16x16x32_bf16 v[108:111], v[160:163], v[192:195], v[108:111]
	v_mfma_f32_16x16x32_bf16 v[100:103], v[152:155], v[200:203], v[100:103]
	v_mfma_f32_16x16x32_bf16 v[92:95], v[160:163], v[200:203], v[92:95]
	v_mfma_f32_16x16x32_bf16 v[84:87], v[152:155], v[212:215], v[84:87]
	v_mfma_f32_16x16x32_bf16 v[76:79], v[160:163], v[212:215], v[76:79]
	v_mfma_f32_16x16x32_bf16 v[124:127], v[156:159], v[188:191], v[124:127]
	v_mfma_f32_16x16x32_bf16 v[120:123], v[164:167], v[188:191], v[120:123]
	v_mfma_f32_16x16x32_bf16 v[116:119], v[156:159], v[196:199], v[116:119]
	v_mfma_f32_16x16x32_bf16 v[108:111], v[164:167], v[196:199], v[108:111]
	v_mfma_f32_16x16x32_bf16 v[100:103], v[156:159], v[204:207], v[100:103]
	v_mfma_f32_16x16x32_bf16 v[92:95], v[164:167], v[204:207], v[92:95]
	v_mfma_f32_16x16x32_bf16 v[84:87], v[156:159], v[216:219], v[84:87]
	v_mfma_f32_16x16x32_bf16 v[76:79], v[164:167], v[216:219], v[76:79]
	s_setprio 0
	s_setprio 1
	v_mfma_f32_16x16x32_bf16 v[112:115], v[168:171], v[184:187], v[112:115]
	v_mfma_f32_16x16x32_bf16 v[104:107], v[176:179], v[184:187], v[104:107]
	v_mfma_f32_16x16x32_bf16 v[96:99], v[168:171], v[192:195], v[96:99]
	v_mfma_f32_16x16x32_bf16 v[88:91], v[176:179], v[192:195], v[88:91]
	v_mfma_f32_16x16x32_bf16 v[80:83], v[168:171], v[200:203], v[80:83]
	v_mfma_f32_16x16x32_bf16 v[72:75], v[176:179], v[200:203], v[72:75]
	v_mfma_f32_16x16x32_bf16 v[68:71], v[168:171], v[212:215], v[68:71]
	v_mfma_f32_16x16x32_bf16 v[64:67], v[176:179], v[212:215], v[64:67]
	v_mfma_f32_16x16x32_bf16 v[112:115], v[172:175], v[188:191], v[112:115]
	v_mfma_f32_16x16x32_bf16 v[104:107], v[180:183], v[188:191], v[104:107]
	v_mfma_f32_16x16x32_bf16 v[96:99], v[172:175], v[196:199], v[96:99]
	v_mfma_f32_16x16x32_bf16 v[88:91], v[180:183], v[196:199], v[88:91]
	v_mfma_f32_16x16x32_bf16 v[80:83], v[172:175], v[204:207], v[80:83]
	v_mfma_f32_16x16x32_bf16 v[72:75], v[180:183], v[204:207], v[72:75]
	v_mfma_f32_16x16x32_bf16 v[68:71], v[172:175], v[216:219], v[68:71]
	v_mfma_f32_16x16x32_bf16 v[64:67], v[180:183], v[216:219], v[64:67]
	s_setprio 0
	s_barrier
	s_add_i32 s30, s85, s3
	v_lshl_add_u64 v[144:145], v[144:145], 0, s[6:7]
	s_mov_b32 m0, s30
	ds_read_b128 v[184:187], v151 offset:49152
	ds_read_b128 v[188:191], v151 offset:50176
	ds_read_b128 v[192:195], v151 offset:51200
	ds_read_b128 v[196:199], v151 offset:52224
	ds_read_b128 v[200:203], v151 offset:53248
	ds_read_b128 v[204:207], v151 offset:54272
	ds_read_b128 v[212:215], v151 offset:55296
	ds_read_b128 v[216:219], v151 offset:56320
	global_load_lds_dwordx4 v[144:145], off
	s_add_i32 m0, s30, 0x2000
	s_add_u32 s28, s28, 0x40080
	v_lshl_add_u64 v[144:145], v[208:209], 0, s[6:7]
	s_addc_u32 s29, s29, 0
	s_add_i32 s30, s86, s3
	global_load_lds_dwordx4 v[144:145], off
	v_lshl_add_u64 v[144:145], s[28:29], 0, v[132:133]
	s_mov_b32 m0, s30
	s_nop 0
	global_load_lds_dwordx4 v[144:145], off
	v_lshl_add_u64 v[144:145], s[28:29], 0, v[128:129]
	s_add_i32 m0, s30, 0x2000
	s_nop 0
	global_load_lds_dwordx4 v[144:145], off
	v_lshl_add_u64 v[144:145], v[220:221], 0, s[6:7]
	s_mov_b32 m0, s58
	s_nop 0
	global_load_lds_dwordx4 v[144:145], off
	v_lshl_add_u64 v[144:145], v[222:223], 0, s[6:7]
	s_mov_b32 m0, s59
	s_nop 0
	global_load_lds_dwordx4 v[144:145], off
	s_waitcnt vmcnt(8)
	s_waitcnt lgkmcnt(0)
	s_barrier
	s_setprio 1
	s_waitcnt lgkmcnt(0)
	v_mfma_f32_16x16x32_bf16 v[60:63], v[152:155], v[184:187], v[60:63]
	v_mfma_f32_16x16x32_bf16 v[56:59], v[160:163], v[184:187], v[56:59]
	v_mfma_f32_16x16x32_bf16 v[52:55], v[152:155], v[192:195], v[52:55]
	v_mfma_f32_16x16x32_bf16 v[44:47], v[160:163], v[192:195], v[44:47]
	v_mfma_f32_16x16x32_bf16 v[36:39], v[152:155], v[200:203], v[36:39]
	v_mfma_f32_16x16x32_bf16 v[28:31], v[160:163], v[200:203], v[28:31]
	v_mfma_f32_16x16x32_bf16 v[20:23], v[152:155], v[212:215], v[20:23]
	v_mfma_f32_16x16x32_bf16 v[12:15], v[160:163], v[212:215], v[12:15]
	v_mfma_f32_16x16x32_bf16 v[60:63], v[156:159], v[188:191], v[60:63]
	v_mfma_f32_16x16x32_bf16 v[56:59], v[164:167], v[188:191], v[56:59]
	v_mfma_f32_16x16x32_bf16 v[52:55], v[156:159], v[196:199], v[52:55]
	v_mfma_f32_16x16x32_bf16 v[44:47], v[164:167], v[196:199], v[44:47]
	v_mfma_f32_16x16x32_bf16 v[36:39], v[156:159], v[204:207], v[36:39]
	v_mfma_f32_16x16x32_bf16 v[28:31], v[164:167], v[204:207], v[28:31]
	v_mfma_f32_16x16x32_bf16 v[20:23], v[156:159], v[216:219], v[20:23]
	v_mfma_f32_16x16x32_bf16 v[12:15], v[164:167], v[216:219], v[12:15]
	s_setprio 0
	s_setprio 1
	v_mfma_f32_16x16x32_bf16 v[48:51], v[168:171], v[184:187], v[48:51]
	v_mfma_f32_16x16x32_bf16 v[40:43], v[176:179], v[184:187], v[40:43]
	v_mfma_f32_16x16x32_bf16 v[32:35], v[168:171], v[192:195], v[32:35]
	v_mfma_f32_16x16x32_bf16 v[24:27], v[176:179], v[192:195], v[24:27]
	v_mfma_f32_16x16x32_bf16 v[16:19], v[168:171], v[200:203], v[16:19]
	v_mfma_f32_16x16x32_bf16 v[8:11], v[176:179], v[200:203], v[8:11]
	v_mfma_f32_16x16x32_bf16 v[4:7], v[168:171], v[212:215], v[4:7]
	v_mfma_f32_16x16x32_bf16 v[0:3], v[176:179], v[212:215], v[0:3]
	v_mfma_f32_16x16x32_bf16 v[48:51], v[172:175], v[188:191], v[48:51]
	v_mfma_f32_16x16x32_bf16 v[40:43], v[180:183], v[188:191], v[40:43]
	v_mfma_f32_16x16x32_bf16 v[32:35], v[172:175], v[196:199], v[32:35]
	v_mfma_f32_16x16x32_bf16 v[24:27], v[180:183], v[196:199], v[24:27]
	v_mfma_f32_16x16x32_bf16 v[16:19], v[172:175], v[204:207], v[16:19]
	v_mfma_f32_16x16x32_bf16 v[8:11], v[180:183], v[204:207], v[8:11]
	v_mfma_f32_16x16x32_bf16 v[4:7], v[172:175], v[216:219], v[4:7]
	v_mfma_f32_16x16x32_bf16 v[0:3], v[180:183], v[216:219], v[0:3]
	s_setprio 0
	s_barrier
	s_add_i32 s84, s84, 2
	s_add_u32 s26, s26, 0x100
	s_addc_u32 s27, s27, 0
	s_add_u32 s82, s82, 0x100
	s_addc_u32 s83, s83, 0
	s_cmp_gt_u32 s84, 13
	s_cbranch_scc0 .LBB0_489
	s_nop 0

; #define PG8_STAGE(bufoff, gbase, voff) do { _Pragma("unroll") for (int _i = 0; _i < 2; ++_i) \
;         __builtin_amdgcn_global_load_lds((const unsigned*)((const char*)(gbase) + (voff)[_i]), (PG8_LAS unsigned*)(lds + (bufoff) + ldsw + _i * 8192), 16, 0, 0); } while (0)
; #define PG8_LDA(dst, b, h) do { _Pragma("unroll") for (int m = 0; m < 4; ++m) _Pragma("unroll") for (int k = 0; k < 2; ++k) dst[m][k] = *(const PG8_LAS bf16x8*)(lds + PG8_SA(b, h) + aoff + m * 2048 + k * 1024); } while (0)
; #define PG8_LDB(dst, b, h) do { _Pragma("unroll") for (int n = 0; n < 2; ++n) _Pragma("unroll") for (int k = 0; k < 2; ++k) dst[n][k] = *(const PG8_LAS bf16x8*)(lds + PG8_SB(b, h) + boff + n * 2048 + k * 1024); } while (0)
; #define PG8_MMA(ai, bj, At, Bt) do { __builtin_amdgcn_s_setprio(1); _Pragma("unroll") for (int m = 0; m < 4; ++m) _Pragma("unroll") for (int n = 0; n < 2; ++n) _Pragma("unroll") for (int k = 0; k < 2; ++k) \
;         acc[ai][bj][m][n] = __builtin_amdgcn_mfma_f32_16x16x32_bf16(Bt[n][k], At[m][k], acc[ai][bj][m][n], 0, 0, 0); __builtin_amdgcn_s_setprio(0); } while (0)
; #define PG8_WAIT_V(n) asm volatile("s_waitcnt vmcnt(" #n ")" ::: "memory")
; #define PG8_WAIT_L(n) asm volatile("s_waitcnt lgkmcnt(" #n ")" ::: "memory")
; template <class Epi, class Sched, bool ALIGN_EPI = false, bool SP2 = false, bool AROWS128 = false>
; __device__ __forceinline__ void gemm_phase(PG8_LAS unsigned char* lds, const Gemm g, const Sched& S, const Epi& E) {
;     ...
;         const bool has_next = S.next(ui + 1, nxt);
;         const char* nA = has_next ? (const char*)g.A + (size_t)nxt.pm * tstep : cA; const char* nB = has_next ? (const char*)g.Bt + (size_t)nxt.pn * tstep : cB;
;         for (int t = 0; t < nt; t += 2) {
;             const bool last = (t == nt - 2);
;             const char* a1 = cA + (size_t)(t + 1) * kstep;
;             const char* a2 = last ? nA : cA + (size_t)(t + 2) * kstep; const char* b2 = last ? nB : cB + (size_t)(t + 2) * kstep;
;             const char* a3 = a2 + kstep; const char* b3 = b2 + kstep;
;             if (last && has_next) S.a_ready(nxt);
;             if constexpr (SP2) {
;             PG8_LDB(B0, 0, 0); PG8_LDB(B1, 0, 1); PG8_SCHED; PG8_LDA(At, 0, 0); PG8_STAGE(PG8_SA(1, 1), a1 + hstepA, voffA);
;             PG8_WAIT_V(8); PG8_WAIT_L(0); PG8_BAR; PG8_MMA(0, 0, At, B0); PG8_MMA(0, 1, At, B1); PG8_BAR; PG8_SCHED;
.LBB0_625:
	v_mov_b32_e32 v236, s16
	v_lshlrev_b32_e32 v236, 9, v236
	v_mov_b32_e32 v237, 0
	v_lshl_add_u64 v[232:233], v[230:231], 0, v[236:237]
	s_lshr_b32 m0, s84, 1
	s_add_i32 m0, m0, 0x21000
	s_mov_b32 exec_hi, 0
	global_load_lds_dwordx4 v[232:233], off
	s_mov_b32 exec_hi, -1
	s_ashr_i32 s55, s54, 31
	s_lshl_b64 s[56:57], s[54:55], 19
	s_add_u32 s56, s46, s56
	s_addc_u32 s57, s47, s57
	s_and_b64 s[58:59], s[14:15], exec
	s_cselect_b32 s17, s57, s19
	s_cselect_b32 s33, s56, s18
	s_ashr_i32 s53, s52, 31
	s_lshl_b64 s[58:59], s[52:53], 19
	s_add_u32 s58, s78, s58
	s_addc_u32 s59, s79, s59
	s_and_b64 s[72:73], s[14:15], exec
	s_cselect_b32 s53, s59, s21
	s_cselect_b32 s55, s58, s20
	s_add_u32 s18, s18, 0x20080
	s_addc_u32 s19, s19, 0
	s_add_u32 s65, s20, 0x100
	v_mov_b32_e32 v0, 0
	s_addc_u32 s72, s21, 0
	s_mov_b32 s73, -2
	v_mov_b64_e32 v[0:1], 0
	v_mov_b64_e32 v[2:3], 0
	v_mov_b64_e32 v[4:5], 0
	v_mov_b64_e32 v[6:7], 0
	v_mov_b64_e32 v[8:9], 0
	v_mov_b64_e32 v[10:11], 0
	v_mov_b64_e32 v[12:13], 0
	v_mov_b64_e32 v[14:15], 0
	v_mov_b64_e32 v[16:17], 0
	v_mov_b64_e32 v[18:19], 0
	v_mov_b64_e32 v[20:21], 0
	v_mov_b64_e32 v[22:23], 0
	v_mov_b64_e32 v[24:25], 0
	v_mov_b64_e32 v[26:27], 0
	v_mov_b64_e32 v[28:29], 0
	v_mov_b64_e32 v[30:31], 0
	v_mov_b64_e32 v[32:33], 0
	v_mov_b64_e32 v[34:35], 0
	v_mov_b64_e32 v[36:37], 0
	v_mov_b64_e32 v[38:39], 0
	v_mov_b64_e32 v[40:41], 0
	v_mov_b64_e32 v[42:43], 0
	v_mov_b64_e32 v[44:45], 0
	v_mov_b64_e32 v[46:47], 0
	v_mov_b64_e32 v[48:49], 0
	v_mov_b64_e32 v[50:51], 0
	v_mov_b64_e32 v[52:53], 0
	v_mov_b64_e32 v[54:55], 0
	v_mov_b64_e32 v[56:57], 0
	v_mov_b64_e32 v[58:59], 0
	v_mov_b64_e32 v[60:61], 0
	v_mov_b64_e32 v[62:63], 0
	v_mov_b64_e32 v[64:65], 0
	v_mov_b64_e32 v[66:67], 0
	v_mov_b64_e32 v[68:69], 0
	v_mov_b64_e32 v[70:71], 0
	v_mov_b64_e32 v[104:105], 0
	v_mov_b64_e32 v[106:107], 0
	v_mov_b64_e32 v[108:109], 0
	v_mov_b64_e32 v[110:111], 0
	v_mov_b64_e32 v[112:113], 0
	v_mov_b64_e32 v[114:115], 0
	v_mov_b64_e32 v[116:117], 0
	v_mov_b64_e32 v[118:119], 0
	v_mov_b64_e32 v[120:121], 0
	v_mov_b64_e32 v[122:123], 0
	v_mov_b64_e32 v[124:125], 0
	v_mov_b64_e32 v[126:127], 0
	v_mov_b64_e32 v[128:129], 0
	v_mov_b64_e32 v[130:131], 0
	v_mov_b64_e32 v[132:133], 0
	v_mov_b64_e32 v[134:135], 0
	v_mov_b64_e32 v[136:137], 0
	v_mov_b64_e32 v[138:139], 0
	v_mov_b64_e32 v[140:141], 0
	v_mov_b64_e32 v[142:143], 0
	v_mov_b64_e32 v[144:145], 0
	v_mov_b64_e32 v[146:147], 0
	v_mov_b64_e32 v[148:149], 0
	v_mov_b64_e32 v[150:151], 0
	v_mov_b64_e32 v[152:153], 0
	v_mov_b64_e32 v[154:155], 0
	v_mov_b64_e32 v[156:157], 0
	v_mov_b64_e32 v[158:159], 0
	ds_read_b128 v[72:75], v207
	ds_read_b128 v[76:79], v207 offset:1024
	ds_read_b128 v[80:83], v207 offset:2048
	ds_read_b128 v[84:87], v207 offset:3072
	ds_read_b128 v[88:91], v208
	ds_read_b128 v[92:95], v208 offset:1024
	ds_read_b128 v[96:99], v208 offset:2048
	ds_read_b128 v[100:103], v208 offset:3072
	s_add_u32 s20, s18, 0xfffe0080
	s_addc_u32 s21, s19, -1
	s_cmp_eq_u32 s73, 12
	s_cselect_b32 s81, s17, s21
	s_cselect_b32 s80, s33, s20
	s_cselect_b32 s21, s53, s72
	s_cselect_b32 s20, s55, s65
	v_lshl_add_u64 v[220:221], s[18:19], 0, v[168:169]
	s_add_i32 m0, s84, 0xc000
	ds_read_b128 v[176:179], v209
	ds_read_b128 v[180:183], v209 offset:1024
	ds_read_b128 v[184:187], v209 offset:2048
	ds_read_b128 v[188:191], v209 offset:3072
	ds_read_b128 v[192:195], v209 offset:4096
	ds_read_b128 v[196:199], v209 offset:5120
	ds_read_b128 v[212:215], v209 offset:6144
	ds_read_b128 v[216:219], v209 offset:7168
	global_load_lds_dwordx4 v[220:221], off
	v_lshl_add_u64 v[220:221], s[18:19], 0, v[170:171]
	s_add_i32 m0, s84, 0xe000
	s_nop 0
	global_load_lds_dwordx4 v[220:221], off
	s_waitcnt vmcnt(8)
	s_waitcnt lgkmcnt(0)
	s_barrier
	s_setprio 1
	s_waitcnt lgkmcnt(0)
	v_mfma_f32_16x16x32_bf16 v[36:39], v[72:75], v[176:179], 0
	v_mfma_f32_16x16x32_bf16 v[28:31], v[80:83], v[176:179], 0
	v_mfma_f32_16x16x32_bf16 v[140:143], v[72:75], v[184:187], 0
	v_mfma_f32_16x16x32_bf16 v[136:139], v[80:83], v[184:187], 0
	v_mfma_f32_16x16x32_bf16 v[124:127], v[72:75], v[192:195], 0
	v_mfma_f32_16x16x32_bf16 v[120:123], v[80:83], v[192:195], 0
	v_mfma_f32_16x16x32_bf16 v[108:111], v[72:75], v[212:215], 0
	v_mfma_f32_16x16x32_bf16 v[104:107], v[80:83], v[212:215], 0
	v_mfma_f32_16x16x32_bf16 v[36:39], v[76:79], v[180:183], v[36:39]
	v_mfma_f32_16x16x32_bf16 v[28:31], v[84:87], v[180:183], v[28:31]
	v_mfma_f32_16x16x32_bf16 v[140:143], v[76:79], v[188:191], v[140:143]
	v_mfma_f32_16x16x32_bf16 v[136:139], v[84:87], v[188:191], v[136:139]
	v_mfma_f32_16x16x32_bf16 v[124:127], v[76:79], v[196:199], v[124:127]
	v_mfma_f32_16x16x32_bf16 v[120:123], v[84:87], v[196:199], v[120:123]
	v_mfma_f32_16x16x32_bf16 v[108:111], v[76:79], v[216:219], v[108:111]
	v_mfma_f32_16x16x32_bf16 v[104:107], v[84:87], v[216:219], v[104:107]
	s_setprio 0
	s_setprio 1
	v_mfma_f32_16x16x32_bf16 v[156:159], v[88:91], v[176:179], 0
	v_mfma_f32_16x16x32_bf16 v[152:155], v[96:99], v[176:179], 0
	v_mfma_f32_16x16x32_bf16 v[148:151], v[88:91], v[184:187], 0
	v_mfma_f32_16x16x32_bf16 v[144:147], v[96:99], v[184:187], 0
	v_mfma_f32_16x16x32_bf16 v[132:135], v[88:91], v[192:195], 0
	v_mfma_f32_16x16x32_bf16 v[128:131], v[96:99], v[192:195], 0
	v_mfma_f32_16x16x32_bf16 v[116:119], v[88:91], v[212:215], 0
	v_mfma_f32_16x16x32_bf16 v[112:115], v[96:99], v[212:215], 0
	v_mfma_f32_16x16x32_bf16 v[156:159], v[92:95], v[180:183], v[156:159]
	v_mfma_f32_16x16x32_bf16 v[152:155], v[100:103], v[180:183], v[152:155]
	v_mfma_f32_16x16x32_bf16 v[148:151], v[92:95], v[188:191], v[148:151]
	v_mfma_f32_16x16x32_bf16 v[144:147], v[100:103], v[188:191], v[144:147]
	v_mfma_f32_16x16x32_bf16 v[132:135], v[92:95], v[196:199], v[132:135]
	v_mfma_f32_16x16x32_bf16 v[128:131], v[100:103], v[196:199], v[128:131]
	v_mfma_f32_16x16x32_bf16 v[116:119], v[92:95], v[216:219], v[116:119]
	v_mfma_f32_16x16x32_bf16 v[112:115], v[100:103], v[216:219], v[112:115]
	s_setprio 0
	s_barrier
; #define PG8_STAGE(bufoff, gbase, voff) do { _Pragma("unroll") for (int _i = 0; _i < 2; ++_i) \
;         __builtin_amdgcn_global_load_lds((const unsigned*)((const char*)(gbase) + (voff)[_i]), (PG8_LAS unsigned*)(lds + (bufoff) + ldsw + _i * 8192), 16, 0, 0); } while (0)
; #define PG8_LDA(dst, b, h) do { _Pragma("unroll") for (int m = 0; m < 4; ++m) _Pragma("unroll") for (int k = 0; k < 2; ++k) dst[m][k] = *(const PG8_LAS bf16x8*)(lds + PG8_SA(b, h) + aoff + m * 2048 + k * 1024); } while (0)
; #define PG8_LDB(dst, b, h) do { _Pragma("unroll") for (int n = 0; n < 2; ++n) _Pragma("unroll") for (int k = 0; k < 2; ++k) dst[n][k] = *(const PG8_LAS bf16x8*)(lds + PG8_SB(b, h) + boff + n * 2048 + k * 1024); } while (0)
; #define PG8_MMA(ai, bj, At, Bt) do { __builtin_amdgcn_s_setprio(1); _Pragma("unroll") for (int m = 0; m < 4; ++m) _Pragma("unroll") for (int n = 0; n < 2; ++n) _Pragma("unroll") for (int k = 0; k < 2; ++k) \
;         acc[ai][bj][m][n] = __builtin_amdgcn_mfma_f32_16x16x32_bf16(Bt[n][k], At[m][k], acc[ai][bj][m][n], 0, 0, 0); __builtin_amdgcn_s_setprio(0); } while (0)
; #define PG8_WAIT_V(n) asm volatile("s_waitcnt vmcnt(" #n ")" ::: "memory")
; #define PG8_WAIT_L(n) asm volatile("s_waitcnt lgkmcnt(" #n ")" ::: "memory")
; #define PG8_BAR __builtin_amdgcn_s_barrier()
; #define PG8_SCHED __builtin_amdgcn_sched_barrier(0)
; template <class Epi, class Sched, bool ALIGN_EPI = false, bool SP2 = false, bool AROWS128 = false>
; __device__ __forceinline__ void gemm_phase(PG8_LAS unsigned char* lds, const Gemm g, const Sched& S, const Epi& E) {
;     ...
;             PG8_LDA(At, 0, 1); PG8_STAGE(PG8_SB(0, 0), b2, voffB); PG8_STAGE(PG8_SB(0, 1), b2 + hstep, voffB); PG8_STAGE(PG8_SA(0, 0), a2, voffA);
;             PG8_WAIT_V(8); PG8_WAIT_L(0); PG8_BAR; PG8_MMA(1, 0, At, B0); PG8_MMA(1, 1, At, B1); PG8_BAR; PG8_SCHED;
;             PG8_LDB(B0, 1, 0); PG8_LDB(B1, 1, 1); PG8_SCHED; PG8_LDA(At, 1, 0); PG8_STAGE(PG8_SA(0, 1), a2 + hstepA, voffA);
;             PG8_WAIT_V(8); PG8_WAIT_L(0); PG8_BAR; PG8_MMA(0, 0, At, B0); PG8_MMA(0, 1, At, B1); PG8_BAR; PG8_SCHED;
	s_add_i32 s76, s3, s35
	v_lshl_add_u64 v[220:221], s[20:21], 0, v[162:163]
	s_mov_b32 m0, s76
	ds_read_b128 v[176:179], v209 offset:16384
	ds_read_b128 v[180:183], v209 offset:17408
	ds_read_b128 v[184:187], v209 offset:18432
	ds_read_b128 v[188:191], v209 offset:19456
	ds_read_b128 v[192:195], v209 offset:20480
	ds_read_b128 v[196:199], v209 offset:21504
	ds_read_b128 v[212:215], v209 offset:22528
	ds_read_b128 v[216:219], v209 offset:23552
	global_load_lds_dwordx4 v[220:221], off
	s_add_i32 m0, s76, 0x2000
	s_add_u32 s76, s20, 0x40000
	v_lshl_add_u64 v[222:223], s[20:21], 0, v[166:167]
	s_addc_u32 s77, s21, 0
	s_add_i32 s82, s95, s35
	global_load_lds_dwordx4 v[222:223], off
	v_lshl_add_u64 v[224:225], s[76:77], 0, v[162:163]
	s_mov_b32 m0, s82
	v_lshl_add_u64 v[226:227], s[80:81], 0, v[164:165]
	global_load_lds_dwordx4 v[224:225], off
	v_lshl_add_u64 v[224:225], s[76:77], 0, v[166:167]
	s_add_i32 m0, s82, 0x2000
	s_nop 0
	global_load_lds_dwordx4 v[224:225], off
	v_lshl_add_u64 v[224:225], s[80:81], 0, v[160:161]
	s_mov_b32 m0, s84
	s_nop 0
	global_load_lds_dwordx4 v[224:225], off
	s_mov_b32 m0, s85
	s_nop 0
	global_load_lds_dwordx4 v[226:227], off
	s_waitcnt vmcnt(8)
	s_waitcnt lgkmcnt(0)
	s_barrier
	s_setprio 1
	s_waitcnt lgkmcnt(0)
	v_mfma_f32_16x16x32_bf16 v[60:63], v[72:75], v[176:179], 0
	v_mfma_f32_16x16x32_bf16 v[56:59], v[80:83], v[176:179], 0
	v_mfma_f32_16x16x32_bf16 v[44:47], v[72:75], v[184:187], 0
	v_mfma_f32_16x16x32_bf16 v[40:43], v[80:83], v[184:187], 0
	v_mfma_f32_16x16x32_bf16 v[20:23], v[72:75], v[192:195], 0
	v_mfma_f32_16x16x32_bf16 v[16:19], v[80:83], v[192:195], 0
	v_mfma_f32_16x16x32_bf16 v[12:15], v[72:75], v[212:215], 0
	v_mfma_f32_16x16x32_bf16 v[8:11], v[80:83], v[212:215], 0
	v_mfma_f32_16x16x32_bf16 v[60:63], v[76:79], v[180:183], v[60:63]
	v_mfma_f32_16x16x32_bf16 v[56:59], v[84:87], v[180:183], v[56:59]
	v_mfma_f32_16x16x32_bf16 v[44:47], v[76:79], v[188:191], v[44:47]
	v_mfma_f32_16x16x32_bf16 v[40:43], v[84:87], v[188:191], v[40:43]
	v_mfma_f32_16x16x32_bf16 v[20:23], v[76:79], v[196:199], v[20:23]
	v_mfma_f32_16x16x32_bf16 v[16:19], v[84:87], v[196:199], v[16:19]
	v_mfma_f32_16x16x32_bf16 v[12:15], v[76:79], v[216:219], v[12:15]
	v_mfma_f32_16x16x32_bf16 v[8:11], v[84:87], v[216:219], v[8:11]
	s_setprio 0
	s_setprio 1
	v_mfma_f32_16x16x32_bf16 v[68:71], v[88:91], v[176:179], 0
	v_mfma_f32_16x16x32_bf16 v[64:67], v[96:99], v[176:179], 0
	v_mfma_f32_16x16x32_bf16 v[52:55], v[88:91], v[184:187], 0
	v_mfma_f32_16x16x32_bf16 v[48:51], v[96:99], v[184:187], 0
	v_mfma_f32_16x16x32_bf16 v[32:35], v[88:91], v[192:195], 0
	v_mfma_f32_16x16x32_bf16 v[24:27], v[96:99], v[192:195], 0
	v_mfma_f32_16x16x32_bf16 v[4:7], v[88:91], v[212:215], 0
	v_mfma_f32_16x16x32_bf16 v[0:3], v[96:99], v[212:215], 0
	v_mfma_f32_16x16x32_bf16 v[68:71], v[92:95], v[180:183], v[68:71]
	v_mfma_f32_16x16x32_bf16 v[64:67], v[100:103], v[180:183], v[64:67]
	v_mfma_f32_16x16x32_bf16 v[52:55], v[92:95], v[188:191], v[52:55]
	v_mfma_f32_16x16x32_bf16 v[48:51], v[100:103], v[188:191], v[48:51]
	v_mfma_f32_16x16x32_bf16 v[32:35], v[92:95], v[196:199], v[32:35]
	v_mfma_f32_16x16x32_bf16 v[24:27], v[100:103], v[196:199], v[24:27]
	v_mfma_f32_16x16x32_bf16 v[4:7], v[92:95], v[216:219], v[4:7]
	v_mfma_f32_16x16x32_bf16 v[0:3], v[100:103], v[216:219], v[0:3]
	s_setprio 0
	s_barrier
	s_add_i32 s82, 0, 0x18000
	s_add_i32 s83, 0, 0x1c000
	v_add_u32_e32 v84, s82, v200
	v_add_u32_e32 v100, s83, v200
	ds_read_b128 v[72:75], v84
	ds_read_b128 v[76:79], v84 offset:1024
	ds_read_b128 v[80:83], v84 offset:2048
	ds_read_b128 v[84:87], v84 offset:3072
	ds_read_b128 v[88:91], v100
	ds_read_b128 v[92:95], v100 offset:1024
	ds_read_b128 v[96:99], v100 offset:2048
	ds_read_b128 v[100:103], v100 offset:3072
	s_add_u32 s76, s80, 0x20000
	s_addc_u32 s77, s81, 0
	s_mov_b32 m0, s86
	v_lshl_add_u64 v[228:229], s[76:77], 0, v[160:161]
	ds_read_b128 v[176:179], v209 offset:32768
	ds_read_b128 v[180:183], v209 offset:33792
	ds_read_b128 v[184:187], v209 offset:34816
	ds_read_b128 v[188:191], v209 offset:35840
	ds_read_b128 v[192:195], v209 offset:36864
	ds_read_b128 v[196:199], v209 offset:37888
	ds_read_b128 v[212:215], v209 offset:38912
	ds_read_b128 v[216:219], v209 offset:39936
	global_load_lds_dwordx4 v[228:229], off
	v_lshl_add_u64 v[228:229], s[76:77], 0, v[164:165]
	s_mov_b32 m0, s87
	s_nop 0
	global_load_lds_dwordx4 v[228:229], off
	s_waitcnt vmcnt(8)
	s_waitcnt lgkmcnt(0)
	s_barrier
; #define PG8_STAGE(bufoff, gbase, voff) do { _Pragma("unroll") for (int _i = 0; _i < 2; ++_i) \
;         __builtin_amdgcn_global_load_lds((const unsigned*)((const char*)(gbase) + (voff)[_i]), (PG8_LAS unsigned*)(lds + (bufoff) + ldsw + _i * 8192), 16, 0, 0); } while (0)
; #define PG8_LDA(dst, b, h) do { _Pragma("unroll") for (int m = 0; m < 4; ++m) _Pragma("unroll") for (int k = 0; k < 2; ++k) dst[m][k] = *(const PG8_LAS bf16x8*)(lds + PG8_SA(b, h) + aoff + m * 2048 + k * 1024); } while (0)
; #define PG8_MMA(ai, bj, At, Bt) do { __builtin_amdgcn_s_setprio(1); _Pragma("unroll") for (int m = 0; m < 4; ++m) _Pragma("unroll") for (int n = 0; n < 2; ++n) _Pragma("unroll") for (int k = 0; k < 2; ++k) \
;         acc[ai][bj][m][n] = __builtin_amdgcn_mfma_f32_16x16x32_bf16(Bt[n][k], At[m][k], acc[ai][bj][m][n], 0, 0, 0); __builtin_amdgcn_s_setprio(0); } while (0)
; #define PG8_WAIT_V(n) asm volatile("s_waitcnt vmcnt(" #n ")" ::: "memory")
; #define PG8_WAIT_L(n) asm volatile("s_waitcnt lgkmcnt(" #n ")" ::: "memory")
; #define PG8_BAR __builtin_amdgcn_s_barrier()
; #define PG8_SCHED __builtin_amdgcn_sched_barrier(0)
; template <class Epi, class Sched, bool ALIGN_EPI = false, bool SP2 = false, bool AROWS128 = false>
; __device__ __forceinline__ void gemm_phase(PG8_LAS unsigned char* lds, const Gemm g, const Sched& S, const Epi& E) {
;     ...
;             PG8_WAIT_V(8); PG8_WAIT_L(0); PG8_BAR; PG8_MMA(0, 0, At, B0); PG8_MMA(0, 1, At, B1); PG8_BAR; PG8_SCHED;
;             PG8_LDA(At, 1, 1); PG8_STAGE(PG8_SB(1, 0), b3, voffB); PG8_STAGE(PG8_SB(1, 1), b3 + hstep, voffB); PG8_STAGE(PG8_SA(1, 0), a3, voffA);
;             PG8_WAIT_V(8); PG8_WAIT_L(0); PG8_BAR; PG8_MMA(1, 0, At, B0); PG8_MMA(1, 1, At, B1); PG8_BAR; PG8_SCHED;
	s_setprio 1
	s_waitcnt lgkmcnt(0)
	v_mfma_f32_16x16x32_bf16 v[36:39], v[72:75], v[176:179], v[36:39]
	v_mfma_f32_16x16x32_bf16 v[28:31], v[80:83], v[176:179], v[28:31]
	v_mfma_f32_16x16x32_bf16 v[140:143], v[72:75], v[184:187], v[140:143]
	v_mfma_f32_16x16x32_bf16 v[136:139], v[80:83], v[184:187], v[136:139]
	v_mfma_f32_16x16x32_bf16 v[124:127], v[72:75], v[192:195], v[124:127]
	v_mfma_f32_16x16x32_bf16 v[120:123], v[80:83], v[192:195], v[120:123]
	v_mfma_f32_16x16x32_bf16 v[108:111], v[72:75], v[212:215], v[108:111]
	v_mfma_f32_16x16x32_bf16 v[104:107], v[80:83], v[212:215], v[104:107]
	v_mfma_f32_16x16x32_bf16 v[36:39], v[76:79], v[180:183], v[36:39]
	v_mfma_f32_16x16x32_bf16 v[28:31], v[84:87], v[180:183], v[28:31]
	v_mfma_f32_16x16x32_bf16 v[140:143], v[76:79], v[188:191], v[140:143]
	v_mfma_f32_16x16x32_bf16 v[136:139], v[84:87], v[188:191], v[136:139]
	v_mfma_f32_16x16x32_bf16 v[124:127], v[76:79], v[196:199], v[124:127]
	v_mfma_f32_16x16x32_bf16 v[120:123], v[84:87], v[196:199], v[120:123]
	v_mfma_f32_16x16x32_bf16 v[108:111], v[76:79], v[216:219], v[108:111]
	v_mfma_f32_16x16x32_bf16 v[104:107], v[84:87], v[216:219], v[104:107]
	s_setprio 0
	s_setprio 1
	v_mfma_f32_16x16x32_bf16 v[156:159], v[88:91], v[176:179], v[156:159]
	v_mfma_f32_16x16x32_bf16 v[152:155], v[96:99], v[176:179], v[152:155]
	v_mfma_f32_16x16x32_bf16 v[148:151], v[88:91], v[184:187], v[148:151]
	v_mfma_f32_16x16x32_bf16 v[144:147], v[96:99], v[184:187], v[144:147]
	v_mfma_f32_16x16x32_bf16 v[132:135], v[88:91], v[192:195], v[132:135]
	v_mfma_f32_16x16x32_bf16 v[128:131], v[96:99], v[192:195], v[128:131]
	v_mfma_f32_16x16x32_bf16 v[116:119], v[88:91], v[212:215], v[116:119]
	v_mfma_f32_16x16x32_bf16 v[112:115], v[96:99], v[212:215], v[112:115]
	v_mfma_f32_16x16x32_bf16 v[156:159], v[92:95], v[180:183], v[156:159]
	v_mfma_f32_16x16x32_bf16 v[152:155], v[100:103], v[180:183], v[152:155]
	v_mfma_f32_16x16x32_bf16 v[148:151], v[92:95], v[188:191], v[148:151]
	v_mfma_f32_16x16x32_bf16 v[144:147], v[100:103], v[188:191], v[144:147]
	v_mfma_f32_16x16x32_bf16 v[132:135], v[92:95], v[196:199], v[132:135]
	v_mfma_f32_16x16x32_bf16 v[128:131], v[100:103], v[196:199], v[128:131]
	v_mfma_f32_16x16x32_bf16 v[116:119], v[92:95], v[216:219], v[116:119]
	v_mfma_f32_16x16x32_bf16 v[112:115], v[100:103], v[216:219], v[112:115]
	s_setprio 0
	s_barrier
	s_add_i32 s76, s82, s35
	v_lshl_add_u64 v[220:221], v[220:221], 0, s[26:27]
	s_mov_b32 m0, s76
	ds_read_b128 v[176:179], v209 offset:49152
	ds_read_b128 v[180:183], v209 offset:50176
	ds_read_b128 v[184:187], v209 offset:51200
	ds_read_b128 v[188:191], v209 offset:52224
	ds_read_b128 v[192:195], v209 offset:53248
	ds_read_b128 v[196:199], v209 offset:54272
	ds_read_b128 v[212:215], v209 offset:55296
	ds_read_b128 v[216:219], v209 offset:56320
	global_load_lds_dwordx4 v[220:221], off
	s_add_i32 m0, s76, 0x2000
	s_add_u32 s20, s20, 0x40080
	v_lshl_add_u64 v[220:221], v[222:223], 0, s[26:27]
	s_addc_u32 s21, s21, 0
	s_add_i32 s76, s83, s35
	global_load_lds_dwordx4 v[220:221], off
	v_lshl_add_u64 v[220:221], s[20:21], 0, v[162:163]
	s_mov_b32 m0, s76
	s_nop 0
	global_load_lds_dwordx4 v[220:221], off
	v_lshl_add_u64 v[220:221], s[20:21], 0, v[166:167]
	s_add_i32 m0, s76, 0x2000
	s_nop 0
	global_load_lds_dwordx4 v[220:221], off
	v_lshl_add_u64 v[220:221], v[224:225], 0, s[26:27]
	s_mov_b32 m0, s89
	s_nop 0
	global_load_lds_dwordx4 v[220:221], off
	v_lshl_add_u64 v[220:221], v[226:227], 0, s[26:27]
	s_mov_b32 m0, s90
	s_nop 0
	global_load_lds_dwordx4 v[220:221], off
	s_waitcnt vmcnt(8)
	s_waitcnt lgkmcnt(0)
	s_barrier
	s_setprio 1
	s_waitcnt lgkmcnt(0)
	v_mfma_f32_16x16x32_bf16 v[60:63], v[72:75], v[176:179], v[60:63]
	v_mfma_f32_16x16x32_bf16 v[56:59], v[80:83], v[176:179], v[56:59]
	v_mfma_f32_16x16x32_bf16 v[44:47], v[72:75], v[184:187], v[44:47]
	v_mfma_f32_16x16x32_bf16 v[40:43], v[80:83], v[184:187], v[40:43]
	v_mfma_f32_16x16x32_bf16 v[20:23], v[72:75], v[192:195], v[20:23]
	v_mfma_f32_16x16x32_bf16 v[16:19], v[80:83], v[192:195], v[16:19]
	v_mfma_f32_16x16x32_bf16 v[12:15], v[72:75], v[212:215], v[12:15]
	v_mfma_f32_16x16x32_bf16 v[8:11], v[80:83], v[212:215], v[8:11]
	v_mfma_f32_16x16x32_bf16 v[60:63], v[76:79], v[180:183], v[60:63]
	v_mfma_f32_16x16x32_bf16 v[56:59], v[84:87], v[180:183], v[56:59]
	v_mfma_f32_16x16x32_bf16 v[44:47], v[76:79], v[188:191], v[44:47]
	v_mfma_f32_16x16x32_bf16 v[40:43], v[84:87], v[188:191], v[40:43]
	v_mfma_f32_16x16x32_bf16 v[20:23], v[76:79], v[196:199], v[20:23]
	v_mfma_f32_16x16x32_bf16 v[16:19], v[84:87], v[196:199], v[16:19]
	v_mfma_f32_16x16x32_bf16 v[12:15], v[76:79], v[216:219], v[12:15]
	v_mfma_f32_16x16x32_bf16 v[8:11], v[84:87], v[216:219], v[8:11]
	s_setprio 0
	s_setprio 1
	v_mfma_f32_16x16x32_bf16 v[68:71], v[88:91], v[176:179], v[68:71]
	v_mfma_f32_16x16x32_bf16 v[64:67], v[96:99], v[176:179], v[64:67]
	v_mfma_f32_16x16x32_bf16 v[52:55], v[88:91], v[184:187], v[52:55]
	v_mfma_f32_16x16x32_bf16 v[48:51], v[96:99], v[184:187], v[48:51]
	v_mfma_f32_16x16x32_bf16 v[32:35], v[88:91], v[192:195], v[32:35]
	v_mfma_f32_16x16x32_bf16 v[24:27], v[96:99], v[192:195], v[24:27]
	v_mfma_f32_16x16x32_bf16 v[4:7], v[88:91], v[212:215], v[4:7]
	v_mfma_f32_16x16x32_bf16 v[0:3], v[96:99], v[212:215], v[0:3]
	v_mfma_f32_16x16x32_bf16 v[68:71], v[92:95], v[180:183], v[68:71]
	v_mfma_f32_16x16x32_bf16 v[64:67], v[100:103], v[180:183], v[64:67]
	v_mfma_f32_16x16x32_bf16 v[52:55], v[92:95], v[188:191], v[52:55]
	v_mfma_f32_16x16x32_bf16 v[48:51], v[100:103], v[188:191], v[48:51]
	v_mfma_f32_16x16x32_bf16 v[32:35], v[92:95], v[196:199], v[32:35]
	v_mfma_f32_16x16x32_bf16 v[24:27], v[100:103], v[196:199], v[24:27]
	v_mfma_f32_16x16x32_bf16 v[4:7], v[92:95], v[216:219], v[4:7]
	v_mfma_f32_16x16x32_bf16 v[0:3], v[100:103], v[216:219], v[0:3]
	s_setprio 0
	s_barrier
	s_add_i32 s73, s73, 2
	s_add_u32 s18, s18, 0x100
	s_addc_u32 s19, s19, 0
	s_add_u32 s65, s65, 0x100
	s_addc_u32 s72, s72, 0
	s_cmp_gt_u32 s73, 13
	s_cbranch_scc0 .LBB0_626
	s_nop 0

; #define PG8_STAGE(bufoff, gbase, voff) do { _Pragma("unroll") for (int _i = 0; _i < 2; ++_i) \
;         __builtin_amdgcn_global_load_lds((const unsigned*)((const char*)(gbase) + (voff)[_i]), (PG8_LAS unsigned*)(lds + (bufoff) + ldsw + _i * 8192), 16, 0, 0); } while (0)
; #define PG8_LDA(dst, b, h) do { _Pragma("unroll") for (int m = 0; m < 4; ++m) _Pragma("unroll") for (int k = 0; k < 2; ++k) dst[m][k] = *(const PG8_LAS bf16x8*)(lds + PG8_SA(b, h) + aoff + m * 2048 + k * 1024); } while (0)
; #define PG8_LDB(dst, b, h) do { _Pragma("unroll") for (int n = 0; n < 2; ++n) _Pragma("unroll") for (int k = 0; k < 2; ++k) dst[n][k] = *(const PG8_LAS bf16x8*)(lds + PG8_SB(b, h) + boff + n * 2048 + k * 1024); } while (0)
; #define PG8_MMA(ai, bj, At, Bt) do { __builtin_amdgcn_s_setprio(1); _Pragma("unroll") for (int m = 0; m < 4; ++m) _Pragma("unroll") for (int n = 0; n < 2; ++n) _Pragma("unroll") for (int k = 0; k < 2; ++k) \
;         acc[ai][bj][m][n] = __builtin_amdgcn_mfma_f32_16x16x32_bf16(Bt[n][k], At[m][k], acc[ai][bj][m][n], 0, 0, 0); __builtin_amdgcn_s_setprio(0); } while (0)
; #define PG8_WAIT_V(n) asm volatile("s_waitcnt vmcnt(" #n ")" ::: "memory")
; #define PG8_WAIT_L(n) asm volatile("s_waitcnt lgkmcnt(" #n ")" ::: "memory")
; template <class Epi, class Sched, bool ALIGN_EPI = false, bool SP2 = false, bool AROWS128 = false>
; __device__ __forceinline__ void gemm_phase(PG8_LAS unsigned char* lds, const Gemm g, const Sched& S, const Epi& E) {
;     ...
;         const bool has_next = S.next(ui + 1, nxt);
;         const char* nA = has_next ? (const char*)g.A + (size_t)nxt.pm * tstep : cA; const char* nB = has_next ? (const char*)g.Bt + (size_t)nxt.pn * tstep : cB;
;         for (int t = 0; t < nt; t += 2) {
;             const bool last = (t == nt - 2);
;             const char* a1 = cA + (size_t)(t + 1) * kstep;
;             const char* a2 = last ? nA : cA + (size_t)(t + 2) * kstep; const char* b2 = last ? nB : cB + (size_t)(t + 2) * kstep;
;             const char* a3 = a2 + kstep; const char* b3 = b2 + kstep;
;             if (last && has_next) S.a_ready(nxt);
;             if constexpr (SP2) {
;             PG8_LDB(B0, 0, 0); PG8_LDB(B1, 0, 1); PG8_SCHED; PG8_LDA(At, 0, 0); PG8_STAGE(PG8_SA(1, 1), a1 + hstepA, voffA);
;             PG8_WAIT_V(8); PG8_WAIT_L(0); PG8_BAR; PG8_MMA(0, 0, At, B0); PG8_MMA(0, 1, At, B1); PG8_BAR; PG8_SCHED;
.LBB0_751:
	s_ashr_i32 s25, s24, 31
	s_lshl_b64 s[26:27], s[24:25], 21
	s_add_u32 s26, s44, s26
	s_addc_u32 s27, s45, s27
	s_and_b64 s[28:29], s[0:1], exec
	s_cselect_b32 s25, s27, s37
	s_cselect_b32 s65, s26, s36
	s_ashr_i32 s21, s20, 31
	s_lshl_b64 s[28:29], s[20:21], 21
	v_readlane_b32 s48, v255, 13
	v_readlane_b32 s49, v255, 14
	s_add_u32 s28, s48, s28
	s_addc_u32 s29, s49, s29
	s_and_b64 s[48:49], s[0:1], exec
	s_cselect_b32 s21, s29, s39
	s_cselect_b32 s72, s28, s38
	s_add_u32 s36, s36, 0x100080
	s_addc_u32 s37, s37, 0
	s_add_u32 s73, s38, 0x100
	v_mov_b32_e32 v0, 0
	s_addc_u32 s76, s39, 0
	s_mov_b32 s77, -2
	v_mov_b64_e32 v[0:1], 0
	v_mov_b64_e32 v[2:3], 0
	v_mov_b64_e32 v[4:5], 0
	v_mov_b64_e32 v[6:7], 0
	v_mov_b64_e32 v[8:9], 0
	v_mov_b64_e32 v[10:11], 0
	v_mov_b64_e32 v[12:13], 0
	v_mov_b64_e32 v[14:15], 0
	v_mov_b64_e32 v[16:17], 0
	v_mov_b64_e32 v[18:19], 0
	v_mov_b64_e32 v[20:21], 0
	v_mov_b64_e32 v[22:23], 0
	v_mov_b64_e32 v[24:25], 0
	v_mov_b64_e32 v[26:27], 0
	v_mov_b64_e32 v[28:29], 0
	v_mov_b64_e32 v[30:31], 0
	v_mov_b64_e32 v[32:33], 0
	v_mov_b64_e32 v[34:35], 0
	v_mov_b64_e32 v[36:37], 0
	v_mov_b64_e32 v[38:39], 0
	v_mov_b64_e32 v[40:41], 0
	v_mov_b64_e32 v[42:43], 0
	v_mov_b64_e32 v[44:45], 0
	v_mov_b64_e32 v[46:47], 0
	v_mov_b64_e32 v[48:49], 0
	v_mov_b64_e32 v[50:51], 0
	v_mov_b64_e32 v[52:53], 0
	v_mov_b64_e32 v[54:55], 0
	v_mov_b64_e32 v[56:57], 0
	v_mov_b64_e32 v[58:59], 0
	v_mov_b64_e32 v[60:61], 0
	v_mov_b64_e32 v[62:63], 0
	v_mov_b64_e32 v[64:65], 0
	v_mov_b64_e32 v[66:67], 0
	v_mov_b64_e32 v[68:69], 0
	v_mov_b64_e32 v[70:71], 0
	v_mov_b64_e32 v[72:73], 0
	v_mov_b64_e32 v[74:75], 0
	v_mov_b64_e32 v[76:77], 0
	v_mov_b64_e32 v[78:79], 0
	v_mov_b64_e32 v[80:81], 0
	v_mov_b64_e32 v[82:83], 0
	v_mov_b64_e32 v[84:85], 0
	v_mov_b64_e32 v[86:87], 0
	v_mov_b64_e32 v[88:89], 0
	v_mov_b64_e32 v[90:91], 0
	v_mov_b64_e32 v[92:93], 0
	v_mov_b64_e32 v[94:95], 0
	v_mov_b64_e32 v[96:97], 0
	v_mov_b64_e32 v[98:99], 0
	v_mov_b64_e32 v[100:101], 0
	v_mov_b64_e32 v[102:103], 0
	v_mov_b64_e32 v[104:105], 0
	v_mov_b64_e32 v[106:107], 0
	v_mov_b64_e32 v[108:109], 0
	v_mov_b64_e32 v[110:111], 0
	v_mov_b64_e32 v[112:113], 0
	v_mov_b64_e32 v[114:115], 0
	v_mov_b64_e32 v[116:117], 0
	v_mov_b64_e32 v[118:119], 0
	v_mov_b64_e32 v[120:121], 0
	v_mov_b64_e32 v[122:123], 0
	v_mov_b64_e32 v[124:125], 0
	v_mov_b64_e32 v[126:127], 0
	ds_read_b128 v[152:155], v149
	ds_read_b128 v[156:159], v149 offset:1024
	ds_read_b128 v[160:163], v149 offset:2048
	ds_read_b128 v[164:167], v149 offset:3072
	ds_read_b128 v[168:171], v150
	ds_read_b128 v[172:175], v150 offset:1024
	ds_read_b128 v[176:179], v150 offset:2048
	ds_read_b128 v[180:183], v150 offset:3072
	s_add_u32 s38, s36, 0xfff00080
	s_addc_u32 s39, s37, -1
	s_cmp_eq_u32 s77, 60
	s_cselect_b32 s49, s25, s39
	s_cselect_b32 s48, s65, s38
	s_cselect_b32 s39, s21, s76
	s_cselect_b32 s38, s72, s73
	v_lshl_add_u64 v[144:145], s[36:37], 0, v[136:137]
	s_add_i32 m0, s31, 0xc000
	ds_read_b128 v[184:187], v151
	ds_read_b128 v[188:191], v151 offset:1024
	ds_read_b128 v[192:195], v151 offset:2048
	ds_read_b128 v[196:199], v151 offset:3072
	ds_read_b128 v[200:203], v151 offset:4096
	ds_read_b128 v[204:207], v151 offset:5120
	ds_read_b128 v[212:215], v151 offset:6144
	ds_read_b128 v[216:219], v151 offset:7168
	global_load_lds_dwordx4 v[144:145], off
	v_lshl_add_u64 v[144:145], s[36:37], 0, v[138:139]
	s_add_i32 m0, s31, 0xe000
	s_nop 0
	global_load_lds_dwordx4 v[144:145], off
	s_waitcnt vmcnt(8)
	s_waitcnt lgkmcnt(0)
	s_barrier
	s_setprio 1
	s_waitcnt lgkmcnt(0)
	v_mfma_f32_16x16x32_bf16 v[124:127], v[152:155], v[184:187], 0
	v_mfma_f32_16x16x32_bf16 v[120:123], v[160:163], v[184:187], 0
	v_mfma_f32_16x16x32_bf16 v[116:119], v[152:155], v[192:195], 0
	v_mfma_f32_16x16x32_bf16 v[108:111], v[160:163], v[192:195], 0
	v_mfma_f32_16x16x32_bf16 v[100:103], v[152:155], v[200:203], 0
	v_mfma_f32_16x16x32_bf16 v[92:95], v[160:163], v[200:203], 0
	v_mfma_f32_16x16x32_bf16 v[84:87], v[152:155], v[212:215], 0
	v_mfma_f32_16x16x32_bf16 v[76:79], v[160:163], v[212:215], 0
	v_mfma_f32_16x16x32_bf16 v[124:127], v[156:159], v[188:191], v[124:127]
	v_mfma_f32_16x16x32_bf16 v[120:123], v[164:167], v[188:191], v[120:123]
	v_mfma_f32_16x16x32_bf16 v[116:119], v[156:159], v[196:199], v[116:119]
	v_mfma_f32_16x16x32_bf16 v[108:111], v[164:167], v[196:199], v[108:111]
	v_mfma_f32_16x16x32_bf16 v[100:103], v[156:159], v[204:207], v[100:103]
	v_mfma_f32_16x16x32_bf16 v[92:95], v[164:167], v[204:207], v[92:95]
	v_mfma_f32_16x16x32_bf16 v[84:87], v[156:159], v[216:219], v[84:87]
	v_mfma_f32_16x16x32_bf16 v[76:79], v[164:167], v[216:219], v[76:79]
	s_setprio 0
	s_setprio 1
	v_mfma_f32_16x16x32_bf16 v[112:115], v[168:171], v[184:187], 0
	v_mfma_f32_16x16x32_bf16 v[104:107], v[176:179], v[184:187], 0
	v_mfma_f32_16x16x32_bf16 v[96:99], v[168:171], v[192:195], 0
	v_mfma_f32_16x16x32_bf16 v[88:91], v[176:179], v[192:195], 0
	v_mfma_f32_16x16x32_bf16 v[80:83], v[168:171], v[200:203], 0
	v_mfma_f32_16x16x32_bf16 v[72:75], v[176:179], v[200:203], 0
	v_mfma_f32_16x16x32_bf16 v[68:71], v[168:171], v[212:215], 0
	v_mfma_f32_16x16x32_bf16 v[64:67], v[176:179], v[212:215], 0
	v_mfma_f32_16x16x32_bf16 v[112:115], v[172:175], v[188:191], v[112:115]
	v_mfma_f32_16x16x32_bf16 v[104:107], v[180:183], v[188:191], v[104:107]
	v_mfma_f32_16x16x32_bf16 v[96:99], v[172:175], v[196:199], v[96:99]
	v_mfma_f32_16x16x32_bf16 v[88:91], v[180:183], v[196:199], v[88:91]
	v_mfma_f32_16x16x32_bf16 v[80:83], v[172:175], v[204:207], v[80:83]
	v_mfma_f32_16x16x32_bf16 v[72:75], v[180:183], v[204:207], v[72:75]
	v_mfma_f32_16x16x32_bf16 v[68:71], v[172:175], v[216:219], v[68:71]
	v_mfma_f32_16x16x32_bf16 v[64:67], v[180:183], v[216:219], v[64:67]
	s_setprio 0
	s_barrier
; #define PG8_STAGE(bufoff, gbase, voff) do { _Pragma("unroll") for (int _i = 0; _i < 2; ++_i) \
;         __builtin_amdgcn_global_load_lds((const unsigned*)((const char*)(gbase) + (voff)[_i]), (PG8_LAS unsigned*)(lds + (bufoff) + ldsw + _i * 8192), 16, 0, 0); } while (0)
; #define PG8_LDA(dst, b, h) do { _Pragma("unroll") for (int m = 0; m < 4; ++m) _Pragma("unroll") for (int k = 0; k < 2; ++k) dst[m][k] = *(const PG8_LAS bf16x8*)(lds + PG8_SA(b, h) + aoff + m * 2048 + k * 1024); } while (0)
; #define PG8_LDB(dst, b, h) do { _Pragma("unroll") for (int n = 0; n < 2; ++n) _Pragma("unroll") for (int k = 0; k < 2; ++k) dst[n][k] = *(const PG8_LAS bf16x8*)(lds + PG8_SB(b, h) + boff + n * 2048 + k * 1024); } while (0)
; #define PG8_MMA(ai, bj, At, Bt) do { __builtin_amdgcn_s_setprio(1); _Pragma("unroll") for (int m = 0; m < 4; ++m) _Pragma("unroll") for (int n = 0; n < 2; ++n) _Pragma("unroll") for (int k = 0; k < 2; ++k) \
;         acc[ai][bj][m][n] = __builtin_amdgcn_mfma_f32_16x16x32_bf16(Bt[n][k], At[m][k], acc[ai][bj][m][n], 0, 0, 0); __builtin_amdgcn_s_setprio(0); } while (0)
; #define PG8_WAIT_V(n) asm volatile("s_waitcnt vmcnt(" #n ")" ::: "memory")
; #define PG8_WAIT_L(n) asm volatile("s_waitcnt lgkmcnt(" #n ")" ::: "memory")
; #define PG8_BAR __builtin_amdgcn_s_barrier()
; #define PG8_SCHED __builtin_amdgcn_sched_barrier(0)
; template <class Epi, class Sched, bool ALIGN_EPI = false, bool SP2 = false, bool AROWS128 = false>
; __device__ __forceinline__ void gemm_phase(PG8_LAS unsigned char* lds, const Gemm g, const Sched& S, const Epi& E) {
;     ...
;             PG8_LDA(At, 0, 1); PG8_STAGE(PG8_SB(0, 0), b2, voffB); PG8_STAGE(PG8_SB(0, 1), b2 + hstep, voffB); PG8_STAGE(PG8_SA(0, 0), a2, voffA);
;             PG8_WAIT_V(8); PG8_WAIT_L(0); PG8_BAR; PG8_MMA(1, 0, At, B0); PG8_MMA(1, 1, At, B1); PG8_BAR; PG8_SCHED;
;             PG8_LDB(B0, 1, 0); PG8_LDB(B1, 1, 1); PG8_SCHED; PG8_LDA(At, 1, 0); PG8_STAGE(PG8_SA(0, 1), a2 + hstepA, voffA);
;             PG8_WAIT_V(8); PG8_WAIT_L(0); PG8_BAR; PG8_MMA(0, 0, At, B0); PG8_MMA(0, 1, At, B1); PG8_BAR; PG8_SCHED;
	s_add_i32 s78, s58, s3
	v_lshl_add_u64 v[144:145], s[38:39], 0, v[132:133]
	s_mov_b32 m0, s78
	ds_read_b128 v[184:187], v151 offset:16384
	ds_read_b128 v[188:191], v151 offset:17408
	ds_read_b128 v[192:195], v151 offset:18432
	ds_read_b128 v[196:199], v151 offset:19456
	ds_read_b128 v[200:203], v151 offset:20480
	ds_read_b128 v[204:207], v151 offset:21504
	ds_read_b128 v[212:215], v151 offset:22528
	ds_read_b128 v[216:219], v151 offset:23552
	global_load_lds_dwordx4 v[144:145], off
	s_add_i32 m0, s78, 0x2000
	s_add_u32 s78, s38, 0x100000
	v_lshl_add_u64 v[208:209], s[38:39], 0, v[128:129]
	s_addc_u32 s79, s39, 0
	s_add_i32 s80, s59, s3
	global_load_lds_dwordx4 v[208:209], off
	v_lshl_add_u64 v[220:221], s[78:79], 0, v[132:133]
	s_mov_b32 m0, s80
	v_lshl_add_u64 v[222:223], s[48:49], 0, v[130:131]
	global_load_lds_dwordx4 v[220:221], off
	v_lshl_add_u64 v[220:221], s[78:79], 0, v[128:129]
	s_add_i32 m0, s80, 0x2000
	s_nop 0
	global_load_lds_dwordx4 v[220:221], off
	v_lshl_add_u64 v[220:221], s[48:49], 0, v[134:135]
	s_mov_b32 m0, s31
	s_nop 0
	global_load_lds_dwordx4 v[220:221], off
	s_mov_b32 m0, s50
	s_nop 0
	global_load_lds_dwordx4 v[222:223], off
	s_waitcnt vmcnt(8)
	s_waitcnt lgkmcnt(0)
	s_barrier
	s_setprio 1
	s_waitcnt lgkmcnt(0)
	v_mfma_f32_16x16x32_bf16 v[60:63], v[152:155], v[184:187], 0
	v_mfma_f32_16x16x32_bf16 v[56:59], v[160:163], v[184:187], 0
	v_mfma_f32_16x16x32_bf16 v[52:55], v[152:155], v[192:195], 0
	v_mfma_f32_16x16x32_bf16 v[44:47], v[160:163], v[192:195], 0
	v_mfma_f32_16x16x32_bf16 v[36:39], v[152:155], v[200:203], 0
	v_mfma_f32_16x16x32_bf16 v[28:31], v[160:163], v[200:203], 0
	v_mfma_f32_16x16x32_bf16 v[20:23], v[152:155], v[212:215], 0
	v_mfma_f32_16x16x32_bf16 v[12:15], v[160:163], v[212:215], 0
	v_mfma_f32_16x16x32_bf16 v[60:63], v[156:159], v[188:191], v[60:63]
	v_mfma_f32_16x16x32_bf16 v[56:59], v[164:167], v[188:191], v[56:59]
	v_mfma_f32_16x16x32_bf16 v[52:55], v[156:159], v[196:199], v[52:55]
	v_mfma_f32_16x16x32_bf16 v[44:47], v[164:167], v[196:199], v[44:47]
	v_mfma_f32_16x16x32_bf16 v[36:39], v[156:159], v[204:207], v[36:39]
	v_mfma_f32_16x16x32_bf16 v[28:31], v[164:167], v[204:207], v[28:31]
	v_mfma_f32_16x16x32_bf16 v[20:23], v[156:159], v[216:219], v[20:23]
	v_mfma_f32_16x16x32_bf16 v[12:15], v[164:167], v[216:219], v[12:15]
	s_setprio 0
	s_setprio 1
	v_mfma_f32_16x16x32_bf16 v[48:51], v[168:171], v[184:187], 0
	v_mfma_f32_16x16x32_bf16 v[40:43], v[176:179], v[184:187], 0
	v_mfma_f32_16x16x32_bf16 v[32:35], v[168:171], v[192:195], 0
	v_mfma_f32_16x16x32_bf16 v[24:27], v[176:179], v[192:195], 0
	v_mfma_f32_16x16x32_bf16 v[16:19], v[168:171], v[200:203], 0
	v_mfma_f32_16x16x32_bf16 v[8:11], v[176:179], v[200:203], 0
	v_mfma_f32_16x16x32_bf16 v[4:7], v[168:171], v[212:215], 0
	v_mfma_f32_16x16x32_bf16 v[0:3], v[176:179], v[212:215], 0
	v_mfma_f32_16x16x32_bf16 v[48:51], v[172:175], v[188:191], v[48:51]
	v_mfma_f32_16x16x32_bf16 v[40:43], v[180:183], v[188:191], v[40:43]
	v_mfma_f32_16x16x32_bf16 v[32:35], v[172:175], v[196:199], v[32:35]
	v_mfma_f32_16x16x32_bf16 v[24:27], v[180:183], v[196:199], v[24:27]
	v_mfma_f32_16x16x32_bf16 v[16:19], v[172:175], v[204:207], v[16:19]
	v_mfma_f32_16x16x32_bf16 v[8:11], v[180:183], v[204:207], v[8:11]
	v_mfma_f32_16x16x32_bf16 v[4:7], v[172:175], v[216:219], v[4:7]
	v_mfma_f32_16x16x32_bf16 v[0:3], v[180:183], v[216:219], v[0:3]
	s_setprio 0
	s_barrier
	s_add_i32 s78, 0, 0x18000
	s_add_i32 s79, 0, 0x1c000
	v_add_u32_e32 v164, s78, v147
	v_add_u32_e32 v180, s79, v147
	ds_read_b128 v[152:155], v164
	ds_read_b128 v[156:159], v164 offset:1024
	ds_read_b128 v[160:163], v164 offset:2048
	ds_read_b128 v[164:167], v164 offset:3072
	ds_read_b128 v[168:171], v180
	ds_read_b128 v[172:175], v180 offset:1024
	ds_read_b128 v[176:179], v180 offset:2048
	ds_read_b128 v[180:183], v180 offset:3072
	s_add_u32 s48, s48, 0x100000
	s_addc_u32 s49, s49, 0
	s_mov_b32 m0, s51
	v_lshl_add_u64 v[224:225], s[48:49], 0, v[134:135]
	ds_read_b128 v[184:187], v151 offset:32768
	ds_read_b128 v[188:191], v151 offset:33792
	ds_read_b128 v[192:195], v151 offset:34816
	ds_read_b128 v[196:199], v151 offset:35840
	ds_read_b128 v[200:203], v151 offset:36864
	ds_read_b128 v[204:207], v151 offset:37888
	ds_read_b128 v[212:215], v151 offset:38912
	ds_read_b128 v[216:219], v151 offset:39936
	global_load_lds_dwordx4 v[224:225], off
	v_lshl_add_u64 v[224:225], s[48:49], 0, v[130:131]
	s_mov_b32 m0, s52
	s_nop 0
	global_load_lds_dwordx4 v[224:225], off
	s_waitcnt vmcnt(8)
	s_waitcnt lgkmcnt(0)
	s_barrier
; #define PG8_STAGE(bufoff, gbase, voff) do { _Pragma("unroll") for (int _i = 0; _i < 2; ++_i) \
;         __builtin_amdgcn_global_load_lds((const unsigned*)((const char*)(gbase) + (voff)[_i]), (PG8_LAS unsigned*)(lds + (bufoff) + ldsw + _i * 8192), 16, 0, 0); } while (0)
; #define PG8_LDA(dst, b, h) do { _Pragma("unroll") for (int m = 0; m < 4; ++m) _Pragma("unroll") for (int k = 0; k < 2; ++k) dst[m][k] = *(const PG8_LAS bf16x8*)(lds + PG8_SA(b, h) + aoff + m * 2048 + k * 1024); } while (0)
; #define PG8_MMA(ai, bj, At, Bt) do { __builtin_amdgcn_s_setprio(1); _Pragma("unroll") for (int m = 0; m < 4; ++m) _Pragma("unroll") for (int n = 0; n < 2; ++n) _Pragma("unroll") for (int k = 0; k < 2; ++k) \
;         acc[ai][bj][m][n] = __builtin_amdgcn_mfma_f32_16x16x32_bf16(Bt[n][k], At[m][k], acc[ai][bj][m][n], 0, 0, 0); __builtin_amdgcn_s_setprio(0); } while (0)
; #define PG8_WAIT_V(n) asm volatile("s_waitcnt vmcnt(" #n ")" ::: "memory")
; #define PG8_WAIT_L(n) asm volatile("s_waitcnt lgkmcnt(" #n ")" ::: "memory")
; #define PG8_BAR __builtin_amdgcn_s_barrier()
; #define PG8_SCHED __builtin_amdgcn_sched_barrier(0)
; template <class Epi, class Sched, bool ALIGN_EPI = false, bool SP2 = false, bool AROWS128 = false>
; __device__ __forceinline__ void gemm_phase(PG8_LAS unsigned char* lds, const Gemm g, const Sched& S, const Epi& E) {
;     ...
;             PG8_WAIT_V(8); PG8_WAIT_L(0); PG8_BAR; PG8_MMA(0, 0, At, B0); PG8_MMA(0, 1, At, B1); PG8_BAR; PG8_SCHED;
;             PG8_LDA(At, 1, 1); PG8_STAGE(PG8_SB(1, 0), b3, voffB); PG8_STAGE(PG8_SB(1, 1), b3 + hstep, voffB); PG8_STAGE(PG8_SA(1, 0), a3, voffA);
;             PG8_WAIT_V(8); PG8_WAIT_L(0); PG8_BAR; PG8_MMA(1, 0, At, B0); PG8_MMA(1, 1, At, B1); PG8_BAR; PG8_SCHED;
	s_setprio 1
	s_waitcnt lgkmcnt(0)
	v_mfma_f32_16x16x32_bf16 v[124:127], v[152:155], v[184:187], v[124:127]
	v_mfma_f32_16x16x32_bf16 v[120:123], v[160:163], v[184:187], v[120:123]
	v_mfma_f32_16x16x32_bf16 v[116:119], v[152:155], v[192:195], v[116:119]
	v_mfma_f32_16x16x32_bf16 v[108:111], v[160:163], v[192:195], v[108:111]
	v_mfma_f32_16x16x32_bf16 v[100:103], v[152:155], v[200:203], v[100:103]
	v_mfma_f32_16x16x32_bf16 v[92:95], v[160:163], v[200:203], v[92:95]
	v_mfma_f32_16x16x32_bf16 v[84:87], v[152:155], v[212:215], v[84:87]
	v_mfma_f32_16x16x32_bf16 v[76:79], v[160:163], v[212:215], v[76:79]
	v_mfma_f32_16x16x32_bf16 v[124:127], v[156:159], v[188:191], v[124:127]
	v_mfma_f32_16x16x32_bf16 v[120:123], v[164:167], v[188:191], v[120:123]
	v_mfma_f32_16x16x32_bf16 v[116:119], v[156:159], v[196:199], v[116:119]
	v_mfma_f32_16x16x32_bf16 v[108:111], v[164:167], v[196:199], v[108:111]
	v_mfma_f32_16x16x32_bf16 v[100:103], v[156:159], v[204:207], v[100:103]
	v_mfma_f32_16x16x32_bf16 v[92:95], v[164:167], v[204:207], v[92:95]
	v_mfma_f32_16x16x32_bf16 v[84:87], v[156:159], v[216:219], v[84:87]
	v_mfma_f32_16x16x32_bf16 v[76:79], v[164:167], v[216:219], v[76:79]
	s_setprio 0
	s_setprio 1
	v_mfma_f32_16x16x32_bf16 v[112:115], v[168:171], v[184:187], v[112:115]
	v_mfma_f32_16x16x32_bf16 v[104:107], v[176:179], v[184:187], v[104:107]
	v_mfma_f32_16x16x32_bf16 v[96:99], v[168:171], v[192:195], v[96:99]
	v_mfma_f32_16x16x32_bf16 v[88:91], v[176:179], v[192:195], v[88:91]
	v_mfma_f32_16x16x32_bf16 v[80:83], v[168:171], v[200:203], v[80:83]
	v_mfma_f32_16x16x32_bf16 v[72:75], v[176:179], v[200:203], v[72:75]
	v_mfma_f32_16x16x32_bf16 v[68:71], v[168:171], v[212:215], v[68:71]
	v_mfma_f32_16x16x32_bf16 v[64:67], v[176:179], v[212:215], v[64:67]
	v_mfma_f32_16x16x32_bf16 v[112:115], v[172:175], v[188:191], v[112:115]
	v_mfma_f32_16x16x32_bf16 v[104:107], v[180:183], v[188:191], v[104:107]
	v_mfma_f32_16x16x32_bf16 v[96:99], v[172:175], v[196:199], v[96:99]
	v_mfma_f32_16x16x32_bf16 v[88:91], v[180:183], v[196:199], v[88:91]
	v_mfma_f32_16x16x32_bf16 v[80:83], v[172:175], v[204:207], v[80:83]
	v_mfma_f32_16x16x32_bf16 v[72:75], v[180:183], v[204:207], v[72:75]
	v_mfma_f32_16x16x32_bf16 v[68:71], v[172:175], v[216:219], v[68:71]
	v_mfma_f32_16x16x32_bf16 v[64:67], v[180:183], v[216:219], v[64:67]
	s_setprio 0
	s_barrier
	s_add_i32 s48, s78, s3
	v_lshl_add_u64 v[144:145], v[144:145], 0, s[8:9]
	s_mov_b32 m0, s48
	ds_read_b128 v[184:187], v151 offset:49152
	ds_read_b128 v[188:191], v151 offset:50176
	ds_read_b128 v[192:195], v151 offset:51200
	ds_read_b128 v[196:199], v151 offset:52224
	ds_read_b128 v[200:203], v151 offset:53248
	ds_read_b128 v[204:207], v151 offset:54272
	ds_read_b128 v[212:215], v151 offset:55296
	ds_read_b128 v[216:219], v151 offset:56320
	global_load_lds_dwordx4 v[144:145], off
	s_add_i32 m0, s48, 0x2000
	s_add_u32 s38, s38, 0x100080
	v_lshl_add_u64 v[144:145], v[208:209], 0, s[8:9]
	s_addc_u32 s39, s39, 0
	s_add_i32 s48, s79, s3
	global_load_lds_dwordx4 v[144:145], off
	v_lshl_add_u64 v[144:145], s[38:39], 0, v[132:133]
	s_mov_b32 m0, s48
	s_nop 0
	global_load_lds_dwordx4 v[144:145], off
	v_lshl_add_u64 v[144:145], s[38:39], 0, v[128:129]
	s_add_i32 m0, s48, 0x2000
	s_nop 0
	global_load_lds_dwordx4 v[144:145], off
	v_lshl_add_u64 v[144:145], v[220:221], 0, s[8:9]
	s_mov_b32 m0, s54
	s_nop 0
	global_load_lds_dwordx4 v[144:145], off
	v_lshl_add_u64 v[144:145], v[222:223], 0, s[8:9]
	s_mov_b32 m0, s55
	s_nop 0
	global_load_lds_dwordx4 v[144:145], off
	s_waitcnt vmcnt(8)
	s_waitcnt lgkmcnt(0)
	s_barrier
	s_setprio 1
	s_waitcnt lgkmcnt(0)
	v_mfma_f32_16x16x32_bf16 v[60:63], v[152:155], v[184:187], v[60:63]
	v_mfma_f32_16x16x32_bf16 v[56:59], v[160:163], v[184:187], v[56:59]
	v_mfma_f32_16x16x32_bf16 v[52:55], v[152:155], v[192:195], v[52:55]
	v_mfma_f32_16x16x32_bf16 v[44:47], v[160:163], v[192:195], v[44:47]
	v_mfma_f32_16x16x32_bf16 v[36:39], v[152:155], v[200:203], v[36:39]
	v_mfma_f32_16x16x32_bf16 v[28:31], v[160:163], v[200:203], v[28:31]
	v_mfma_f32_16x16x32_bf16 v[20:23], v[152:155], v[212:215], v[20:23]
	v_mfma_f32_16x16x32_bf16 v[12:15], v[160:163], v[212:215], v[12:15]
	v_mfma_f32_16x16x32_bf16 v[60:63], v[156:159], v[188:191], v[60:63]
	v_mfma_f32_16x16x32_bf16 v[56:59], v[164:167], v[188:191], v[56:59]
	v_mfma_f32_16x16x32_bf16 v[52:55], v[156:159], v[196:199], v[52:55]
	v_mfma_f32_16x16x32_bf16 v[44:47], v[164:167], v[196:199], v[44:47]
	v_mfma_f32_16x16x32_bf16 v[36:39], v[156:159], v[204:207], v[36:39]
	v_mfma_f32_16x16x32_bf16 v[28:31], v[164:167], v[204:207], v[28:31]
	v_mfma_f32_16x16x32_bf16 v[20:23], v[156:159], v[216:219], v[20:23]
	v_mfma_f32_16x16x32_bf16 v[12:15], v[164:167], v[216:219], v[12:15]
	s_setprio 0
	s_setprio 1
	v_mfma_f32_16x16x32_bf16 v[48:51], v[168:171], v[184:187], v[48:51]
	v_mfma_f32_16x16x32_bf16 v[40:43], v[176:179], v[184:187], v[40:43]
	v_mfma_f32_16x16x32_bf16 v[32:35], v[168:171], v[192:195], v[32:35]
	v_mfma_f32_16x16x32_bf16 v[24:27], v[176:179], v[192:195], v[24:27]
	v_mfma_f32_16x16x32_bf16 v[16:19], v[168:171], v[200:203], v[16:19]
	v_mfma_f32_16x16x32_bf16 v[8:11], v[176:179], v[200:203], v[8:11]
	v_mfma_f32_16x16x32_bf16 v[4:7], v[168:171], v[212:215], v[4:7]
	v_mfma_f32_16x16x32_bf16 v[0:3], v[176:179], v[212:215], v[0:3]
	v_mfma_f32_16x16x32_bf16 v[48:51], v[172:175], v[188:191], v[48:51]
	v_mfma_f32_16x16x32_bf16 v[40:43], v[180:183], v[188:191], v[40:43]
	v_mfma_f32_16x16x32_bf16 v[32:35], v[172:175], v[196:199], v[32:35]
	v_mfma_f32_16x16x32_bf16 v[24:27], v[180:183], v[196:199], v[24:27]
	v_mfma_f32_16x16x32_bf16 v[16:19], v[172:175], v[204:207], v[16:19]
	v_mfma_f32_16x16x32_bf16 v[8:11], v[180:183], v[204:207], v[8:11]
	v_mfma_f32_16x16x32_bf16 v[4:7], v[172:175], v[216:219], v[4:7]
	v_mfma_f32_16x16x32_bf16 v[0:3], v[180:183], v[216:219], v[0:3]
	s_setprio 0
	s_barrier
	s_add_i32 s77, s77, 2
	s_add_u32 s36, s36, 0x100
	s_addc_u32 s37, s37, 0
	s_add_u32 s73, s73, 0x100
	s_addc_u32 s76, s76, 0
	s_cmp_gt_u32 s77, 61
	s_cbranch_scc0 .LBB0_752
	s_nop 0

; #define PG8_STAGE(bufoff, gbase, voff) do { _Pragma("unroll") for (int _i = 0; _i < 2; ++_i) \
;         __builtin_amdgcn_global_load_lds((const unsigned*)((const char*)(gbase) + (voff)[_i]), (PG8_LAS unsigned*)(lds + (bufoff) + ldsw + _i * 8192), 16, 0, 0); } while (0)
; #define PG8_LDA(dst, b, h) do { _Pragma("unroll") for (int m = 0; m < 4; ++m) _Pragma("unroll") for (int k = 0; k < 2; ++k) dst[m][k] = *(const PG8_LAS bf16x8*)(lds + PG8_SA(b, h) + aoff + m * 2048 + k * 1024); } while (0)
; #define PG8_LDB(dst, b, h) do { _Pragma("unroll") for (int n = 0; n < 2; ++n) _Pragma("unroll") for (int k = 0; k < 2; ++k) dst[n][k] = *(const PG8_LAS bf16x8*)(lds + PG8_SB(b, h) + boff + n * 2048 + k * 1024); } while (0)
; #define PG8_MMA(ai, bj, At, Bt) do { __builtin_amdgcn_s_setprio(1); _Pragma("unroll") for (int m = 0; m < 4; ++m) _Pragma("unroll") for (int n = 0; n < 2; ++n) _Pragma("unroll") for (int k = 0; k < 2; ++k) \
;         acc[ai][bj][m][n] = __builtin_amdgcn_mfma_f32_16x16x32_bf16(Bt[n][k], At[m][k], acc[ai][bj][m][n], 0, 0, 0); __builtin_amdgcn_s_setprio(0); } while (0)
; #define PG8_WAIT_V(n) asm volatile("s_waitcnt vmcnt(" #n ")" ::: "memory")
; #define PG8_WAIT_L(n) asm volatile("s_waitcnt lgkmcnt(" #n ")" ::: "memory")
; template <class Epi, class Sched, bool ALIGN_EPI = false, bool SP2 = false, bool AROWS128 = false>
; __device__ __forceinline__ void gemm_phase(PG8_LAS unsigned char* lds, const Gemm g, const Sched& S, const Epi& E) {
;     ...
;         const bool has_next = S.next(ui + 1, nxt);
;         const char* nA = has_next ? (const char*)g.A + (size_t)nxt.pm * tstep : cA; const char* nB = has_next ? (const char*)g.Bt + (size_t)nxt.pn * tstep : cB;
;         for (int t = 0; t < nt; t += 2) {
;             const bool last = (t == nt - 2);
;             const char* a1 = cA + (size_t)(t + 1) * kstep;
;             const char* a2 = last ? nA : cA + (size_t)(t + 2) * kstep; const char* b2 = last ? nB : cB + (size_t)(t + 2) * kstep;
;             const char* a3 = a2 + kstep; const char* b3 = b2 + kstep;
;             if (last && has_next) S.a_ready(nxt);
;             if constexpr (SP2) {
;             PG8_LDB(B0, 0, 0); PG8_LDB(B1, 0, 1); PG8_SCHED; PG8_LDA(At, 0, 0); PG8_STAGE(PG8_SA(1, 1), a1 + hstepA, voffA);
;             PG8_WAIT_V(8); PG8_WAIT_L(0); PG8_BAR; PG8_MMA(0, 0, At, B0); PG8_MMA(0, 1, At, B1); PG8_BAR; PG8_SCHED;
.LBB0_885:
	s_ashr_i32 s31, s30, 31
	s_lshl_b64 s[36:37], s[30:31], 19
	s_add_u32 s36, s44, s36
	s_addc_u32 s37, s45, s37
	s_and_b64 s[38:39], s[0:1], exec
	s_cselect_b32 s31, s37, s43
	s_cselect_b32 s65, s36, s42
	s_ashr_i32 s29, s28, 31
	s_lshl_b64 s[38:39], s[28:29], 19
	s_add_u32 s38, s8, s38
	s_addc_u32 s39, s9, s39
	s_and_b64 s[48:49], s[0:1], exec
	s_cselect_b32 s29, s39, s47
	s_cselect_b32 s66, s38, s46
	s_add_u32 s42, s42, 0x40080
	s_addc_u32 s43, s43, 0
	s_add_u32 s67, s46, 0x100
	v_mov_b32_e32 v0, 0
	s_addc_u32 s72, s47, 0
	s_mov_b32 s73, -2
	v_mov_b64_e32 v[0:1], 0
	v_mov_b64_e32 v[2:3], 0
	v_mov_b64_e32 v[4:5], 0
	v_mov_b64_e32 v[6:7], 0
	v_mov_b64_e32 v[8:9], 0
	v_mov_b64_e32 v[10:11], 0
	v_mov_b64_e32 v[12:13], 0
	v_mov_b64_e32 v[14:15], 0
	v_mov_b64_e32 v[16:17], 0
	v_mov_b64_e32 v[18:19], 0
	v_mov_b64_e32 v[20:21], 0
	v_mov_b64_e32 v[22:23], 0
	v_mov_b64_e32 v[24:25], 0
	v_mov_b64_e32 v[26:27], 0
	v_mov_b64_e32 v[28:29], 0
	v_mov_b64_e32 v[30:31], 0
	v_mov_b64_e32 v[32:33], 0
	v_mov_b64_e32 v[34:35], 0
	v_mov_b64_e32 v[36:37], 0
	v_mov_b64_e32 v[38:39], 0
	v_mov_b64_e32 v[40:41], 0
	v_mov_b64_e32 v[42:43], 0
	v_mov_b64_e32 v[44:45], 0
	v_mov_b64_e32 v[46:47], 0
	v_mov_b64_e32 v[48:49], 0
	v_mov_b64_e32 v[50:51], 0
	v_mov_b64_e32 v[52:53], 0
	v_mov_b64_e32 v[54:55], 0
	v_mov_b64_e32 v[56:57], 0
	v_mov_b64_e32 v[58:59], 0
	v_mov_b64_e32 v[60:61], 0
	v_mov_b64_e32 v[62:63], 0
	v_mov_b64_e32 v[64:65], 0
	v_mov_b64_e32 v[66:67], 0
	v_mov_b64_e32 v[68:69], 0
	v_mov_b64_e32 v[70:71], 0
	v_mov_b64_e32 v[72:73], 0
	v_mov_b64_e32 v[74:75], 0
	v_mov_b64_e32 v[76:77], 0
	v_mov_b64_e32 v[78:79], 0
	v_mov_b64_e32 v[80:81], 0
	v_mov_b64_e32 v[82:83], 0
	v_mov_b64_e32 v[84:85], 0
	v_mov_b64_e32 v[86:87], 0
	v_mov_b64_e32 v[88:89], 0
	v_mov_b64_e32 v[90:91], 0
	v_mov_b64_e32 v[92:93], 0
	v_mov_b64_e32 v[94:95], 0
	v_mov_b64_e32 v[96:97], 0
	v_mov_b64_e32 v[98:99], 0
	v_mov_b64_e32 v[100:101], 0
	v_mov_b64_e32 v[102:103], 0
	v_mov_b64_e32 v[104:105], 0
	v_mov_b64_e32 v[106:107], 0
	v_mov_b64_e32 v[108:109], 0
	v_mov_b64_e32 v[110:111], 0
	v_mov_b64_e32 v[112:113], 0
	v_mov_b64_e32 v[114:115], 0
	v_mov_b64_e32 v[116:117], 0
	v_mov_b64_e32 v[118:119], 0
	v_mov_b64_e32 v[120:121], 0
	v_mov_b64_e32 v[122:123], 0
	v_mov_b64_e32 v[124:125], 0
	v_mov_b64_e32 v[126:127], 0
	ds_read_b128 v[152:155], v149
	ds_read_b128 v[156:159], v149 offset:1024
	ds_read_b128 v[160:163], v149 offset:2048
	ds_read_b128 v[164:167], v149 offset:3072
	ds_read_b128 v[168:171], v150
	ds_read_b128 v[172:175], v150 offset:1024
	ds_read_b128 v[176:179], v150 offset:2048
	ds_read_b128 v[180:183], v150 offset:3072
	s_add_u32 s46, s42, 0xfffc0080
	s_addc_u32 s47, s43, -1
	s_cmp_eq_u32 s73, 12
	s_cselect_b32 s49, s31, s47
	s_cselect_b32 s48, s65, s46
	s_cselect_b32 s47, s29, s72
	s_cselect_b32 s46, s66, s67
	v_lshl_add_u64 v[144:145], s[42:43], 0, v[136:137]
	s_add_i32 m0, s41, 0xc000
	ds_read_b128 v[184:187], v151
	ds_read_b128 v[188:191], v151 offset:1024
	ds_read_b128 v[192:195], v151 offset:2048
	ds_read_b128 v[196:199], v151 offset:3072
	ds_read_b128 v[200:203], v151 offset:4096
	ds_read_b128 v[204:207], v151 offset:5120
	ds_read_b128 v[212:215], v151 offset:6144
	ds_read_b128 v[216:219], v151 offset:7168
	global_load_lds_dwordx4 v[144:145], off
	v_lshl_add_u64 v[144:145], s[42:43], 0, v[138:139]
	s_add_i32 m0, s41, 0xe000
	s_nop 0
	global_load_lds_dwordx4 v[144:145], off
	s_waitcnt vmcnt(8)
	s_waitcnt lgkmcnt(0)
	s_barrier
	s_setprio 1
	s_waitcnt lgkmcnt(0)
	v_mfma_f32_16x16x32_bf16 v[124:127], v[152:155], v[184:187], 0
	v_mfma_f32_16x16x32_bf16 v[120:123], v[160:163], v[184:187], 0
	v_mfma_f32_16x16x32_bf16 v[116:119], v[152:155], v[192:195], 0
	v_mfma_f32_16x16x32_bf16 v[108:111], v[160:163], v[192:195], 0
	v_mfma_f32_16x16x32_bf16 v[100:103], v[152:155], v[200:203], 0
	v_mfma_f32_16x16x32_bf16 v[92:95], v[160:163], v[200:203], 0
	v_mfma_f32_16x16x32_bf16 v[84:87], v[152:155], v[212:215], 0
	v_mfma_f32_16x16x32_bf16 v[76:79], v[160:163], v[212:215], 0
	v_mfma_f32_16x16x32_bf16 v[124:127], v[156:159], v[188:191], v[124:127]
	v_mfma_f32_16x16x32_bf16 v[120:123], v[164:167], v[188:191], v[120:123]
	v_mfma_f32_16x16x32_bf16 v[116:119], v[156:159], v[196:199], v[116:119]
	v_mfma_f32_16x16x32_bf16 v[108:111], v[164:167], v[196:199], v[108:111]
	v_mfma_f32_16x16x32_bf16 v[100:103], v[156:159], v[204:207], v[100:103]
	v_mfma_f32_16x16x32_bf16 v[92:95], v[164:167], v[204:207], v[92:95]
	v_mfma_f32_16x16x32_bf16 v[84:87], v[156:159], v[216:219], v[84:87]
	v_mfma_f32_16x16x32_bf16 v[76:79], v[164:167], v[216:219], v[76:79]
	s_setprio 0
	s_setprio 1
	v_mfma_f32_16x16x32_bf16 v[112:115], v[168:171], v[184:187], 0
	v_mfma_f32_16x16x32_bf16 v[104:107], v[176:179], v[184:187], 0
	v_mfma_f32_16x16x32_bf16 v[96:99], v[168:171], v[192:195], 0
	v_mfma_f32_16x16x32_bf16 v[88:91], v[176:179], v[192:195], 0
	v_mfma_f32_16x16x32_bf16 v[80:83], v[168:171], v[200:203], 0
	v_mfma_f32_16x16x32_bf16 v[72:75], v[176:179], v[200:203], 0
	v_mfma_f32_16x16x32_bf16 v[68:71], v[168:171], v[212:215], 0
	v_mfma_f32_16x16x32_bf16 v[64:67], v[176:179], v[212:215], 0
	v_mfma_f32_16x16x32_bf16 v[112:115], v[172:175], v[188:191], v[112:115]
	v_mfma_f32_16x16x32_bf16 v[104:107], v[180:183], v[188:191], v[104:107]
	v_mfma_f32_16x16x32_bf16 v[96:99], v[172:175], v[196:199], v[96:99]
	v_mfma_f32_16x16x32_bf16 v[88:91], v[180:183], v[196:199], v[88:91]
	v_mfma_f32_16x16x32_bf16 v[80:83], v[172:175], v[204:207], v[80:83]
	v_mfma_f32_16x16x32_bf16 v[72:75], v[180:183], v[204:207], v[72:75]
	v_mfma_f32_16x16x32_bf16 v[68:71], v[172:175], v[216:219], v[68:71]
	v_mfma_f32_16x16x32_bf16 v[64:67], v[180:183], v[216:219], v[64:67]
	s_setprio 0
	s_barrier
; #define PG8_STAGE(bufoff, gbase, voff) do { _Pragma("unroll") for (int _i = 0; _i < 2; ++_i) \
;         __builtin_amdgcn_global_load_lds((const unsigned*)((const char*)(gbase) + (voff)[_i]), (PG8_LAS unsigned*)(lds + (bufoff) + ldsw + _i * 8192), 16, 0, 0); } while (0)
; #define PG8_LDA(dst, b, h) do { _Pragma("unroll") for (int m = 0; m < 4; ++m) _Pragma("unroll") for (int k = 0; k < 2; ++k) dst[m][k] = *(const PG8_LAS bf16x8*)(lds + PG8_SA(b, h) + aoff + m * 2048 + k * 1024); } while (0)
; #define PG8_LDB(dst, b, h) do { _Pragma("unroll") for (int n = 0; n < 2; ++n) _Pragma("unroll") for (int k = 0; k < 2; ++k) dst[n][k] = *(const PG8_LAS bf16x8*)(lds + PG8_SB(b, h) + boff + n * 2048 + k * 1024); } while (0)
; #define PG8_MMA(ai, bj, At, Bt) do { __builtin_amdgcn_s_setprio(1); _Pragma("unroll") for (int m = 0; m < 4; ++m) _Pragma("unroll") for (int n = 0; n < 2; ++n) _Pragma("unroll") for (int k = 0; k < 2; ++k) \
;         acc[ai][bj][m][n] = __builtin_amdgcn_mfma_f32_16x16x32_bf16(Bt[n][k], At[m][k], acc[ai][bj][m][n], 0, 0, 0); __builtin_amdgcn_s_setprio(0); } while (0)
; #define PG8_WAIT_V(n) asm volatile("s_waitcnt vmcnt(" #n ")" ::: "memory")
; #define PG8_WAIT_L(n) asm volatile("s_waitcnt lgkmcnt(" #n ")" ::: "memory")
; #define PG8_BAR __builtin_amdgcn_s_barrier()
; #define PG8_SCHED __builtin_amdgcn_sched_barrier(0)
; template <class Epi, class Sched, bool ALIGN_EPI = false, bool SP2 = false, bool AROWS128 = false>
; __device__ __forceinline__ void gemm_phase(PG8_LAS unsigned char* lds, const Gemm g, const Sched& S, const Epi& E) {
;     ...
;             PG8_LDA(At, 0, 1); PG8_STAGE(PG8_SB(0, 0), b2, voffB); PG8_STAGE(PG8_SB(0, 1), b2 + hstep, voffB); PG8_STAGE(PG8_SA(0, 0), a2, voffA);
;             PG8_WAIT_V(8); PG8_WAIT_L(0); PG8_BAR; PG8_MMA(1, 0, At, B0); PG8_MMA(1, 1, At, B1); PG8_BAR; PG8_SCHED;
;             PG8_LDB(B0, 1, 0); PG8_LDB(B1, 1, 1); PG8_SCHED; PG8_LDA(At, 1, 0); PG8_STAGE(PG8_SA(0, 1), a2 + hstepA, voffA);
;             PG8_WAIT_V(8); PG8_WAIT_L(0); PG8_BAR; PG8_MMA(0, 0, At, B0); PG8_MMA(0, 1, At, B1); PG8_BAR; PG8_SCHED;
	s_add_i32 s76, s58, s3
	v_lshl_add_u64 v[144:145], s[46:47], 0, v[132:133]
	s_mov_b32 m0, s76
	ds_read_b128 v[184:187], v151 offset:16384
	ds_read_b128 v[188:191], v151 offset:17408
	ds_read_b128 v[192:195], v151 offset:18432
	ds_read_b128 v[196:199], v151 offset:19456
	ds_read_b128 v[200:203], v151 offset:20480
	ds_read_b128 v[204:207], v151 offset:21504
	ds_read_b128 v[212:215], v151 offset:22528
	ds_read_b128 v[216:219], v151 offset:23552
	global_load_lds_dwordx4 v[144:145], off
	s_add_i32 m0, s76, 0x2000
	s_add_u32 s76, s46, 0x40000
	v_lshl_add_u64 v[208:209], s[46:47], 0, v[128:129]
	s_addc_u32 s77, s47, 0
	s_add_i32 s78, s59, s3
	global_load_lds_dwordx4 v[208:209], off
	v_lshl_add_u64 v[220:221], s[76:77], 0, v[132:133]
	s_mov_b32 m0, s78
	v_lshl_add_u64 v[222:223], s[48:49], 0, v[130:131]
	global_load_lds_dwordx4 v[220:221], off
	v_lshl_add_u64 v[220:221], s[76:77], 0, v[128:129]
	s_add_i32 m0, s78, 0x2000
	s_nop 0
	global_load_lds_dwordx4 v[220:221], off
	v_lshl_add_u64 v[220:221], s[48:49], 0, v[134:135]
	s_mov_b32 m0, s41
	s_nop 0
	global_load_lds_dwordx4 v[220:221], off
	s_mov_b32 m0, s50
	s_nop 0
	global_load_lds_dwordx4 v[222:223], off
	s_waitcnt vmcnt(8)
	s_waitcnt lgkmcnt(0)
	s_barrier
	s_setprio 1
	s_waitcnt lgkmcnt(0)
	v_mfma_f32_16x16x32_bf16 v[60:63], v[152:155], v[184:187], 0
	v_mfma_f32_16x16x32_bf16 v[56:59], v[160:163], v[184:187], 0
	v_mfma_f32_16x16x32_bf16 v[52:55], v[152:155], v[192:195], 0
	v_mfma_f32_16x16x32_bf16 v[44:47], v[160:163], v[192:195], 0
	v_mfma_f32_16x16x32_bf16 v[36:39], v[152:155], v[200:203], 0
	v_mfma_f32_16x16x32_bf16 v[28:31], v[160:163], v[200:203], 0
	v_mfma_f32_16x16x32_bf16 v[20:23], v[152:155], v[212:215], 0
	v_mfma_f32_16x16x32_bf16 v[12:15], v[160:163], v[212:215], 0
	v_mfma_f32_16x16x32_bf16 v[60:63], v[156:159], v[188:191], v[60:63]
	v_mfma_f32_16x16x32_bf16 v[56:59], v[164:167], v[188:191], v[56:59]
	v_mfma_f32_16x16x32_bf16 v[52:55], v[156:159], v[196:199], v[52:55]
	v_mfma_f32_16x16x32_bf16 v[44:47], v[164:167], v[196:199], v[44:47]
	v_mfma_f32_16x16x32_bf16 v[36:39], v[156:159], v[204:207], v[36:39]
	v_mfma_f32_16x16x32_bf16 v[28:31], v[164:167], v[204:207], v[28:31]
	v_mfma_f32_16x16x32_bf16 v[20:23], v[156:159], v[216:219], v[20:23]
	v_mfma_f32_16x16x32_bf16 v[12:15], v[164:167], v[216:219], v[12:15]
	s_setprio 0
	s_setprio 1
	v_mfma_f32_16x16x32_bf16 v[48:51], v[168:171], v[184:187], 0
	v_mfma_f32_16x16x32_bf16 v[40:43], v[176:179], v[184:187], 0
	v_mfma_f32_16x16x32_bf16 v[32:35], v[168:171], v[192:195], 0
	v_mfma_f32_16x16x32_bf16 v[24:27], v[176:179], v[192:195], 0
	v_mfma_f32_16x16x32_bf16 v[16:19], v[168:171], v[200:203], 0
	v_mfma_f32_16x16x32_bf16 v[8:11], v[176:179], v[200:203], 0
	v_mfma_f32_16x16x32_bf16 v[4:7], v[168:171], v[212:215], 0
	v_mfma_f32_16x16x32_bf16 v[0:3], v[176:179], v[212:215], 0
	v_mfma_f32_16x16x32_bf16 v[48:51], v[172:175], v[188:191], v[48:51]
	v_mfma_f32_16x16x32_bf16 v[40:43], v[180:183], v[188:191], v[40:43]
	v_mfma_f32_16x16x32_bf16 v[32:35], v[172:175], v[196:199], v[32:35]
	v_mfma_f32_16x16x32_bf16 v[24:27], v[180:183], v[196:199], v[24:27]
	v_mfma_f32_16x16x32_bf16 v[16:19], v[172:175], v[204:207], v[16:19]
	v_mfma_f32_16x16x32_bf16 v[8:11], v[180:183], v[204:207], v[8:11]
	v_mfma_f32_16x16x32_bf16 v[4:7], v[172:175], v[216:219], v[4:7]
	v_mfma_f32_16x16x32_bf16 v[0:3], v[180:183], v[216:219], v[0:3]
	s_setprio 0
	s_barrier
	s_add_i32 s76, 0, 0x18000
	s_add_i32 s77, 0, 0x1c000
	v_add_u32_e32 v164, s76, v147
	v_add_u32_e32 v180, s77, v147
	ds_read_b128 v[152:155], v164
	ds_read_b128 v[156:159], v164 offset:1024
	ds_read_b128 v[160:163], v164 offset:2048
	ds_read_b128 v[164:167], v164 offset:3072
	ds_read_b128 v[168:171], v180
	ds_read_b128 v[172:175], v180 offset:1024
	ds_read_b128 v[176:179], v180 offset:2048
	ds_read_b128 v[180:183], v180 offset:3072
	s_add_u32 s48, s48, 0x40000
	s_addc_u32 s49, s49, 0
	s_mov_b32 m0, s51
	v_lshl_add_u64 v[224:225], s[48:49], 0, v[134:135]
	ds_read_b128 v[184:187], v151 offset:32768
	ds_read_b128 v[188:191], v151 offset:33792
	ds_read_b128 v[192:195], v151 offset:34816
	ds_read_b128 v[196:199], v151 offset:35840
	ds_read_b128 v[200:203], v151 offset:36864
	ds_read_b128 v[204:207], v151 offset:37888
	ds_read_b128 v[212:215], v151 offset:38912
	ds_read_b128 v[216:219], v151 offset:39936
	global_load_lds_dwordx4 v[224:225], off
	v_lshl_add_u64 v[224:225], s[48:49], 0, v[130:131]
	s_mov_b32 m0, s52
	s_nop 0
	global_load_lds_dwordx4 v[224:225], off
	s_waitcnt vmcnt(8)
	s_waitcnt lgkmcnt(0)
	s_barrier
; #define PG8_STAGE(bufoff, gbase, voff) do { _Pragma("unroll") for (int _i = 0; _i < 2; ++_i) \
;         __builtin_amdgcn_global_load_lds((const unsigned*)((const char*)(gbase) + (voff)[_i]), (PG8_LAS unsigned*)(lds + (bufoff) + ldsw + _i * 8192), 16, 0, 0); } while (0)
; #define PG8_LDA(dst, b, h) do { _Pragma("unroll") for (int m = 0; m < 4; ++m) _Pragma("unroll") for (int k = 0; k < 2; ++k) dst[m][k] = *(const PG8_LAS bf16x8*)(lds + PG8_SA(b, h) + aoff + m * 2048 + k * 1024); } while (0)
; #define PG8_MMA(ai, bj, At, Bt) do { __builtin_amdgcn_s_setprio(1); _Pragma("unroll") for (int m = 0; m < 4; ++m) _Pragma("unroll") for (int n = 0; n < 2; ++n) _Pragma("unroll") for (int k = 0; k < 2; ++k) \
;         acc[ai][bj][m][n] = __builtin_amdgcn_mfma_f32_16x16x32_bf16(Bt[n][k], At[m][k], acc[ai][bj][m][n], 0, 0, 0); __builtin_amdgcn_s_setprio(0); } while (0)
; #define PG8_WAIT_V(n) asm volatile("s_waitcnt vmcnt(" #n ")" ::: "memory")
; #define PG8_WAIT_L(n) asm volatile("s_waitcnt lgkmcnt(" #n ")" ::: "memory")
; #define PG8_BAR __builtin_amdgcn_s_barrier()
; #define PG8_SCHED __builtin_amdgcn_sched_barrier(0)
; template <class Epi, class Sched, bool ALIGN_EPI = false, bool SP2 = false, bool AROWS128 = false>
; __device__ __forceinline__ void gemm_phase(PG8_LAS unsigned char* lds, const Gemm g, const Sched& S, const Epi& E) {
;     ...
;             PG8_WAIT_V(8); PG8_WAIT_L(0); PG8_BAR; PG8_MMA(0, 0, At, B0); PG8_MMA(0, 1, At, B1); PG8_BAR; PG8_SCHED;
;             PG8_LDA(At, 1, 1); PG8_STAGE(PG8_SB(1, 0), b3, voffB); PG8_STAGE(PG8_SB(1, 1), b3 + hstep, voffB); PG8_STAGE(PG8_SA(1, 0), a3, voffA);
;             PG8_WAIT_V(8); PG8_WAIT_L(0); PG8_BAR; PG8_MMA(1, 0, At, B0); PG8_MMA(1, 1, At, B1); PG8_BAR; PG8_SCHED;
	s_setprio 1
	s_waitcnt lgkmcnt(0)
	v_mfma_f32_16x16x32_bf16 v[124:127], v[152:155], v[184:187], v[124:127]
	v_mfma_f32_16x16x32_bf16 v[120:123], v[160:163], v[184:187], v[120:123]
	v_mfma_f32_16x16x32_bf16 v[116:119], v[152:155], v[192:195], v[116:119]
	v_mfma_f32_16x16x32_bf16 v[108:111], v[160:163], v[192:195], v[108:111]
	v_mfma_f32_16x16x32_bf16 v[100:103], v[152:155], v[200:203], v[100:103]
	v_mfma_f32_16x16x32_bf16 v[92:95], v[160:163], v[200:203], v[92:95]
	v_mfma_f32_16x16x32_bf16 v[84:87], v[152:155], v[212:215], v[84:87]
	v_mfma_f32_16x16x32_bf16 v[76:79], v[160:163], v[212:215], v[76:79]
	v_mfma_f32_16x16x32_bf16 v[124:127], v[156:159], v[188:191], v[124:127]
	v_mfma_f32_16x16x32_bf16 v[120:123], v[164:167], v[188:191], v[120:123]
	v_mfma_f32_16x16x32_bf16 v[116:119], v[156:159], v[196:199], v[116:119]
	v_mfma_f32_16x16x32_bf16 v[108:111], v[164:167], v[196:199], v[108:111]
	v_mfma_f32_16x16x32_bf16 v[100:103], v[156:159], v[204:207], v[100:103]
	v_mfma_f32_16x16x32_bf16 v[92:95], v[164:167], v[204:207], v[92:95]
	v_mfma_f32_16x16x32_bf16 v[84:87], v[156:159], v[216:219], v[84:87]
	v_mfma_f32_16x16x32_bf16 v[76:79], v[164:167], v[216:219], v[76:79]
	s_setprio 0
	s_setprio 1
	v_mfma_f32_16x16x32_bf16 v[112:115], v[168:171], v[184:187], v[112:115]
	v_mfma_f32_16x16x32_bf16 v[104:107], v[176:179], v[184:187], v[104:107]
	v_mfma_f32_16x16x32_bf16 v[96:99], v[168:171], v[192:195], v[96:99]
	v_mfma_f32_16x16x32_bf16 v[88:91], v[176:179], v[192:195], v[88:91]
	v_mfma_f32_16x16x32_bf16 v[80:83], v[168:171], v[200:203], v[80:83]
	v_mfma_f32_16x16x32_bf16 v[72:75], v[176:179], v[200:203], v[72:75]
	v_mfma_f32_16x16x32_bf16 v[68:71], v[168:171], v[212:215], v[68:71]
	v_mfma_f32_16x16x32_bf16 v[64:67], v[176:179], v[212:215], v[64:67]
	v_mfma_f32_16x16x32_bf16 v[112:115], v[172:175], v[188:191], v[112:115]
	v_mfma_f32_16x16x32_bf16 v[104:107], v[180:183], v[188:191], v[104:107]
	v_mfma_f32_16x16x32_bf16 v[96:99], v[172:175], v[196:199], v[96:99]
	v_mfma_f32_16x16x32_bf16 v[88:91], v[180:183], v[196:199], v[88:91]
	v_mfma_f32_16x16x32_bf16 v[80:83], v[172:175], v[204:207], v[80:83]
	v_mfma_f32_16x16x32_bf16 v[72:75], v[180:183], v[204:207], v[72:75]
	v_mfma_f32_16x16x32_bf16 v[68:71], v[172:175], v[216:219], v[68:71]
	v_mfma_f32_16x16x32_bf16 v[64:67], v[180:183], v[216:219], v[64:67]
	s_setprio 0
	s_barrier
	s_add_i32 s48, s76, s3
	v_lshl_add_u64 v[144:145], v[144:145], 0, s[16:17]
	s_mov_b32 m0, s48
	ds_read_b128 v[184:187], v151 offset:49152
	ds_read_b128 v[188:191], v151 offset:50176
	ds_read_b128 v[192:195], v151 offset:51200
	ds_read_b128 v[196:199], v151 offset:52224
	ds_read_b128 v[200:203], v151 offset:53248
	ds_read_b128 v[204:207], v151 offset:54272
	ds_read_b128 v[212:215], v151 offset:55296
	ds_read_b128 v[216:219], v151 offset:56320
	global_load_lds_dwordx4 v[144:145], off
	s_add_i32 m0, s48, 0x2000
	s_add_u32 s46, s46, 0x40080
	v_lshl_add_u64 v[144:145], v[208:209], 0, s[16:17]
	s_addc_u32 s47, s47, 0
	s_add_i32 s48, s77, s3
	global_load_lds_dwordx4 v[144:145], off
	v_lshl_add_u64 v[144:145], s[46:47], 0, v[132:133]
	s_mov_b32 m0, s48
	s_nop 0
	global_load_lds_dwordx4 v[144:145], off
	v_lshl_add_u64 v[144:145], s[46:47], 0, v[128:129]
	s_add_i32 m0, s48, 0x2000
	s_nop 0
	global_load_lds_dwordx4 v[144:145], off
	v_lshl_add_u64 v[144:145], v[220:221], 0, s[16:17]
	s_mov_b32 m0, s54
	s_nop 0
	global_load_lds_dwordx4 v[144:145], off
	v_lshl_add_u64 v[144:145], v[222:223], 0, s[16:17]
	s_mov_b32 m0, s55
	s_nop 0
	global_load_lds_dwordx4 v[144:145], off
	s_waitcnt vmcnt(8)
	s_waitcnt lgkmcnt(0)
	s_barrier
	s_setprio 1
	s_waitcnt lgkmcnt(0)
	v_mfma_f32_16x16x32_bf16 v[60:63], v[152:155], v[184:187], v[60:63]
	v_mfma_f32_16x16x32_bf16 v[56:59], v[160:163], v[184:187], v[56:59]
	v_mfma_f32_16x16x32_bf16 v[52:55], v[152:155], v[192:195], v[52:55]
	v_mfma_f32_16x16x32_bf16 v[44:47], v[160:163], v[192:195], v[44:47]
	v_mfma_f32_16x16x32_bf16 v[36:39], v[152:155], v[200:203], v[36:39]
	v_mfma_f32_16x16x32_bf16 v[28:31], v[160:163], v[200:203], v[28:31]
	v_mfma_f32_16x16x32_bf16 v[20:23], v[152:155], v[212:215], v[20:23]
	v_mfma_f32_16x16x32_bf16 v[12:15], v[160:163], v[212:215], v[12:15]
	v_mfma_f32_16x16x32_bf16 v[60:63], v[156:159], v[188:191], v[60:63]
	v_mfma_f32_16x16x32_bf16 v[56:59], v[164:167], v[188:191], v[56:59]
	v_mfma_f32_16x16x32_bf16 v[52:55], v[156:159], v[196:199], v[52:55]
	v_mfma_f32_16x16x32_bf16 v[44:47], v[164:167], v[196:199], v[44:47]
	v_mfma_f32_16x16x32_bf16 v[36:39], v[156:159], v[204:207], v[36:39]
	v_mfma_f32_16x16x32_bf16 v[28:31], v[164:167], v[204:207], v[28:31]
	v_mfma_f32_16x16x32_bf16 v[20:23], v[156:159], v[216:219], v[20:23]
	v_mfma_f32_16x16x32_bf16 v[12:15], v[164:167], v[216:219], v[12:15]
	s_setprio 0
	s_setprio 1
	v_mfma_f32_16x16x32_bf16 v[48:51], v[168:171], v[184:187], v[48:51]
	v_mfma_f32_16x16x32_bf16 v[40:43], v[176:179], v[184:187], v[40:43]
	v_mfma_f32_16x16x32_bf16 v[32:35], v[168:171], v[192:195], v[32:35]
	v_mfma_f32_16x16x32_bf16 v[24:27], v[176:179], v[192:195], v[24:27]
	v_mfma_f32_16x16x32_bf16 v[16:19], v[168:171], v[200:203], v[16:19]
	v_mfma_f32_16x16x32_bf16 v[8:11], v[176:179], v[200:203], v[8:11]
	v_mfma_f32_16x16x32_bf16 v[4:7], v[168:171], v[212:215], v[4:7]
	v_mfma_f32_16x16x32_bf16 v[0:3], v[176:179], v[212:215], v[0:3]
	v_mfma_f32_16x16x32_bf16 v[48:51], v[172:175], v[188:191], v[48:51]
	v_mfma_f32_16x16x32_bf16 v[40:43], v[180:183], v[188:191], v[40:43]
	v_mfma_f32_16x16x32_bf16 v[32:35], v[172:175], v[196:199], v[32:35]
	v_mfma_f32_16x16x32_bf16 v[24:27], v[180:183], v[196:199], v[24:27]
	v_mfma_f32_16x16x32_bf16 v[16:19], v[172:175], v[204:207], v[16:19]
	v_mfma_f32_16x16x32_bf16 v[8:11], v[180:183], v[204:207], v[8:11]
	v_mfma_f32_16x16x32_bf16 v[4:7], v[172:175], v[216:219], v[4:7]
	v_mfma_f32_16x16x32_bf16 v[0:3], v[180:183], v[216:219], v[0:3]
	s_setprio 0
	s_barrier
	s_add_i32 s73, s73, 2
	s_add_u32 s42, s42, 0x100
	s_addc_u32 s43, s43, 0
	s_add_u32 s67, s67, 0x100
	s_addc_u32 s72, s72, 0
	s_cmp_gt_u32 s73, 13
	s_cbranch_scc0 .LBB0_886
	s_nop 0
